# opt12: + rowwise phases: flat->global ops, single late vmcnt wait with all stores after it (trans hazard nop kept)
# baseline (speedup 1.0000x reference)
; template <bool HAS_H, bool HAS_XN, int XL, int XS>
; __device__ __forceinline__ void rowwise_phase(const float* xf, half_t* x16, float* xo, const half_t* hs, const float* nwA, const float* gvec, const float* nwB, const float* scv, const float* shv, half_t* xn, int gw, int NW, int lane) {
;     ...
;         f32x4 wA[4], gg[4], wB[4], sc1[4], sh[4];
; #pragma unroll
;         for (int j = 0; j < 4; ++j) {
;             if (HAS_H) { wA[j] = *((const f32x4*)nwA + lane + 64 * j); gg[j] = *((const f32x4*)(gvec + (size_t)b * 6144) + lane + 64 * j); }
;             if (HAS_XN) { wB[j] = *((const f32x4*)nwB + lane + 64 * j); sc1[j] = *((const f32x4*)(scv + (size_t)b * 6144) + lane + 64 * j) + 1.0f; sh[j] = *((const f32x4*)(shv + (size_t)b * 6144) + lane + 64 * j); }
;         }
;         const int mend = (b + 1) * S;
;         f32x4 xq[4]; half4 xh[4], hq[4];
;         {
;             const int m0 = b * S + gw;
;             if (m0 < mend) {
;                 if (XL == 0) { const f32x4* xr = (const f32x4*)(xf + (size_t)m0 * D) + lane;
; #pragma unroll
;                     for (int j = 0; j < 4; ++j) xq[j] = xr[64 * j]; }
;                 else { const half4* xr = (const half4*)(x16 + (size_t)m0 * D) + lane;
; #pragma unroll
;                     for (int j = 0; j < 4; ++j) xh[j] = xr[64 * j]; }
;                 if (HAS_H) { const half4* hr = (const half4*)(hs + (size_t)m0 * D) + lane;
; #pragma unroll
;                     for (int j = 0; j < 4; ++j) hq[j] = hr[64 * j]; }
;             }
;         }
;         for (int m = b * S + gw; m < mend; m += NW) {
;             f32x4 xv[4]; half4 hcur[4];
; #pragma unroll
;             for (int j = 0; j < 4; ++j) { if (XL == 0) xv[j] = xq[j]; else xv[j] = (f32x4){(float)xh[j][0], (float)xh[j][1], (float)xh[j][2], (float)xh[j][3]}; if (HAS_H) hcur[j] = hq[j]; }
;             const int mn = (m + NW < mend) ? m + NW : m;
;             {
;                 if (XL == 0) { const f32x4* xr = (const f32x4*)(xf + (size_t)mn * D) + lane;
; #pragma unroll
;                     for (int j = 0; j < 4; ++j) xq[j] = xr[64 * j]; }
;                 else { const half4* xr = (const half4*)(x16 + (size_t)mn * D) + lane;
; #pragma unroll
;                     for (int j = 0; j < 4; ++j) xh[j] = xr[64 * j]; }
;                 if (HAS_H) { const half4* hr = (const half4*)(hs + (size_t)mn * D) + lane;
; #pragma unroll
.LBB0_109:
	s_or_b64 exec, exec, s[0:1]
	v_readlane_b32 s2, v253, 0
	v_readlane_b32 s3, v253, 1
	v_mov_b32_e32 v16, v170
	s_mov_b32 s8, s77
	s_load_dwordx2 s[0:1], s[2:3], 0x98
	s_waitcnt lgkmcnt(0)
	s_load_dwordx2 s[4:5], s[2:3], 0x38
	v_and_b32_e32 v18, 63, v16
	v_lshlrev_b32_e32 v58, 4, v18
	s_waitcnt lgkmcnt(0)
	global_load_dwordx4 v[0:3], v58, s[4:5]
	global_load_dwordx4 v[4:7], v58, s[4:5] offset:1024
	global_load_dwordx4 v[8:11], v58, s[4:5] offset:2048
	global_load_dwordx4 v[12:15], v58, s[4:5] offset:3072
	s_load_dwordx2 s[6:7], s[2:3], 0x0
	v_readfirstlane_b32 s2, v16
	s_ashr_i32 s2, s2, 6
	s_lshl_b32 s3, s8, 3
	v_mov_b32_e32 v59, 0
	s_add_i32 s2, s2, s3
	v_lshl_add_u64 v[16:17], s[0:1], 0, v[58:59]
	s_mov_b64 s[8:9], 0x4501000
	v_lshl_add_u64 v[54:55], v[16:17], 0, s[8:9]
	s_mov_b64 s[8:9], 0x4500000
	s_cmpk_lt_i32 s2, 0x4000
	v_lshl_add_u64 v[52:53], v[16:17], 0, s[8:9]
	s_waitcnt lgkmcnt(0)
	v_lshl_add_u64 v[48:49], s[6:7], 0, v[58:59]
	s_cselect_b64 s[8:9], -1, 0
	s_cmpk_gt_i32 s2, 0x3fff
	v_mbcnt_lo_u32_b32 v76, -1, 0
	v_lshlrev_b32_e32 v50, 3, v18
	s_cbranch_scc1 .LBB0_113
	global_load_dwordx4 v[62:65], v[54:55], off
	global_load_dwordx4 v[66:69], v[54:55], off offset:1024
	global_load_dwordx4 v[16:19], v[52:53], off
	global_load_dwordx4 v[20:23], v[52:53], off offset:1024
	global_load_dwordx4 v[70:73], v[54:55], off offset:2048
	global_load_dwordx4 v[86:89], v[54:55], off offset:3072
	s_ashr_i32 s3, s2, 31
	s_lshl_b64 s[6:7], s[2:3], 12
	v_lshl_add_u64 v[56:57], v[48:49], 0, s[6:7]
	global_load_dwordx4 v[40:43], v[56:57], off offset:2048
	global_load_dwordx4 v[32:35], v[56:57], off offset:3072
	global_load_dwordx4 v[24:27], v[52:53], off offset:2048
	global_load_dwordx4 v[28:31], v[52:53], off offset:3072
	global_load_dwordx4 v[36:39], v[56:57], off
	global_load_dwordx4 v[44:47], v[56:57], off offset:1024
	v_lshl_add_u64 v[56:57], s[4:5], 0, v[58:59]
	v_mbcnt_hi_u32_b32 v58, -1, v76
	v_mov_b32_e32 v51, v59
	v_and_b32_e32 v59, 64, v58
	v_xor_b32_e32 v60, 1, v58
	v_add_u32_e32 v59, 64, v59
	v_xor_b32_e32 v61, 2, v58
	v_cmp_lt_i32_e32 vcc, v60, v59
	v_xor_b32_e32 v74, 4, v58
	v_xor_b32_e32 v75, 8, v58
	v_cndmask_b32_e32 v60, v58, v60, vcc
	v_cmp_lt_i32_e32 vcc, v61, v59
	v_xor_b32_e32 v79, 16, v58
	v_xor_b32_e32 v80, 32, v58
	v_cndmask_b32_e32 v61, v58, v61, vcc
	v_cmp_lt_i32_e32 vcc, v74, v59
	s_lshl_b64 s[6:7], s[2:3], 11
	s_add_u32 s6, s0, s6
	v_cndmask_b32_e32 v74, v58, v74, vcc
	v_cmp_lt_i32_e32 vcc, v75, v59
	s_addc_u32 s7, s1, s7
	s_mov_b64 s[4:5], 0x4800000
	v_cndmask_b32_e32 v75, v58, v75, vcc
	v_cmp_lt_i32_e32 vcc, v79, v59
	s_ashr_i32 s81, s80, 31
	v_mov_b32_e32 v77, 0x358637bd
	v_cndmask_b32_e32 v83, v58, v79, vcc
	v_cmp_lt_i32_e32 vcc, v80, v59
	s_mov_b32 s12, 0xf800000
	v_mov_b32_e32 v78, 0x260
	v_cndmask_b32_e32 v58, v58, v80, vcc
	v_lshlrev_b32_e32 v84, 2, v58
	v_lshl_add_u64 v[58:59], s[6:7], 0, v[50:51]
	s_mov_b32 s13, s2
	v_lshlrev_b32_e32 v79, 2, v60
	v_lshlrev_b32_e32 v80, 2, v61
	v_lshlrev_b32_e32 v81, 2, v74
	v_lshlrev_b32_e32 v82, 2, v75
	v_lshlrev_b32_e32 v83, 2, v83
	s_lshl_b64 s[10:11], s[80:81], 11
	v_lshl_add_u64 v[58:59], v[58:59], 0, s[4:5]
	s_waitcnt vmcnt(0) lgkmcnt(0)
	v_pk_add_f32 v[60:61], v[64:65], 1.0 op_sel_hi:[1,0]
	v_pk_add_f32 v[62:63], v[62:63], 1.0 op_sel_hi:[1,0]
	v_pk_add_f32 v[64:65], v[68:69], 1.0 op_sel_hi:[1,0]
	v_pk_add_f32 v[66:67], v[66:67], 1.0 op_sel_hi:[1,0]
	v_pk_add_f32 v[68:69], v[72:73], 1.0 op_sel_hi:[1,0]
	v_pk_add_f32 v[70:71], v[70:71], 1.0 op_sel_hi:[1,0]
	v_pk_add_f32 v[72:73], v[88:89], 1.0 op_sel_hi:[1,0]
	v_pk_add_f32 v[74:75], v[86:87], 1.0 op_sel_hi:[1,0]
	v_mov_b32_e32 v86, v32
	v_mov_b32_e32 v87, v33
	v_mov_b32_e32 v51, v34
	v_mov_b32_e32 v85, v35
.LBB0_111:
	s_add_i32 s3, s13, s80
	v_pk_mul_f32 v[88:89], v[46:47], v[46:47]
	v_pk_mul_f32 v[90:91], v[44:45], v[44:45]
	v_pk_mul_f32 v[92:93], v[38:39], v[38:39]
	v_pk_mul_f32 v[94:95], v[36:37], v[36:37]
	s_cmpk_lt_i32 s3, 0x4000
	v_mul_f32_e32 v96, v40, v40
	v_mul_f32_e32 v98, v42, v42
	v_pk_mov_b32 v[100:101], v[94:95], v[92:93] op_sel:[1,0]
	v_mov_b32_e32 v95, v93
	v_pk_mov_b32 v[92:93], v[90:91], v[88:89] op_sel:[1,0]
	v_mov_b32_e32 v91, v89
	s_cselect_b64 s[4:5], -1, 0
	v_pk_fma_f32 v[88:89], v[40:41], v[40:41], v[96:97] op_sel_hi:[1,1,0]
	v_pk_fma_f32 v[96:97], v[42:43], v[42:43], v[98:99] op_sel_hi:[1,1,0]
	v_pk_add_f32 v[94:95], v[100:101], v[94:95]
	v_pk_add_f32 v[90:91], v[92:93], v[90:91]
	s_and_b64 s[4:5], s[4:5], exec
	v_mul_f32_e32 v88, v86, v86
	v_mul_f32_e32 v96, v87, v87
	v_pk_add_f32 v[86:87], v[94:95], v[94:95] op_sel_hi:[0,1]
	v_pk_add_f32 v[90:91], v[90:91], v[90:91] op_sel_hi:[0,1]
	s_cselect_b32 s6, s3, s13
	v_mul_f32_e32 v86, v51, v51
	v_mul_f32_e32 v90, v85, v85
	s_ashr_i32 s7, s6, 31
	v_pk_add_f32 v[88:89], v[88:89], v[96:97]
	v_pk_add_f32 v[86:87], v[86:87], v[90:91]
	s_lshl_b64 s[6:7], s[6:7], 12
	v_pk_add_f32 v[86:87], v[88:89], v[86:87]
	v_lshl_add_u64 v[102:103], v[48:49], 0, s[6:7]
	v_add_f32_e32 v51, v86, v87
	global_load_dwordx4 v[86:89], v[102:103], off
	global_load_dwordx4 v[90:93], v[102:103], off offset:1024
	global_load_dwordx4 v[94:97], v[102:103], off offset:3072
	global_load_dwordx4 v[98:101], v[102:103], off offset:2048
	ds_bpermute_b32 v85, v79, v51
	s_mov_b32 s13, s3
	s_waitcnt lgkmcnt(0)
	v_add_f32_e32 v51, v51, v85
	ds_bpermute_b32 v85, v80, v51
	s_waitcnt lgkmcnt(0)
	v_add_f32_e32 v51, v51, v85
	ds_bpermute_b32 v85, v81, v51
	s_waitcnt lgkmcnt(0)
	v_add_f32_e32 v51, v51, v85
	ds_bpermute_b32 v85, v82, v51
	s_waitcnt lgkmcnt(0)
	v_add_f32_e32 v51, v51, v85
	ds_bpermute_b32 v85, v83, v51
	s_waitcnt lgkmcnt(0)
	v_add_f32_e32 v51, v51, v85
	ds_bpermute_b32 v85, v84, v51
	s_waitcnt lgkmcnt(0)
; template <bool HAS_H, bool HAS_XN, int XL, int XS>
; __device__ __forceinline__ void rowwise_phase(const float* xf, half_t* x16, float* xo, const half_t* hs, const float* nwA, const float* gvec, const float* nwB, const float* scv, const float* shv, half_t* xn, int gw, int NW, int lane) {
;     ...
;         for (int m = b * S + gw; m < mend; m += NW) {
;             f32x4 xv[4]; half4 hcur[4];
; #pragma unroll
;             for (int j = 0; j < 4; ++j) { if (XL == 0) xv[j] = xq[j]; else xv[j] = (f32x4){(float)xh[j][0], (float)xh[j][1], (float)xh[j][2], (float)xh[j][3]}; if (HAS_H) hcur[j] = hq[j]; }
;             const int mn = (m + NW < mend) ? m + NW : m;
;             {
;                 if (XL == 0) { const f32x4* xr = (const f32x4*)(xf + (size_t)mn * D) + lane;
; #pragma unroll
;                     for (int j = 0; j < 4; ++j) xq[j] = xr[64 * j]; }
;                 else { const half4* xr = (const half4*)(x16 + (size_t)mn * D) + lane;
; #pragma unroll
;                     for (int j = 0; j < 4; ++j) xh[j] = xr[64 * j]; }
;                 if (HAS_H) { const half4* hr = (const half4*)(hs + (size_t)mn * D) + lane;
; #pragma unroll
;                     for (int j = 0; j < 4; ++j) hq[j] = hr[64 * j]; }
;             }
;             if (HAS_H) {
;                 f32x4 hv[4]; float ss = 0.f;
; #pragma unroll
;                 for (int j = 0; j < 4; ++j) { const half4 h4 = hcur[j]; hv[j] = (f32x4){(float)h4[0], (float)h4[1], (float)h4[2], (float)h4[3]}; ss += (hv[j][0] * hv[j][0] + hv[j][1] * hv[j][1]) + (hv[j][2] * hv[j][2] + hv[j][3] * hv[j][3]); }
;                 const float r = 1.0f / sqrtf(wave_sum(ss) * (1.f / D) + RMS_EPS);
; #pragma unroll
;                 for (int j = 0; j < 4; ++j) xv[j] = xv[j] + gg[j] * (hv[j] * r * wA[j]);
;             }
;             if (XS == 1) {
;                 u32x2* xs = (u32x2*)(x16 + (size_t)m * D) + lane;
; #pragma unroll
;                 for (int j = 0; j < 4; ++j) { u32x2 pk; pk.x = pg8::pkh(xv[j][0], xv[j][1]); pk.y = pg8::pkh(xv[j][2], xv[j][3]); xs[64 * j] = pk; }
;             } else if (XS == 2) {
;                 f32x4* xs = (f32x4*)(xo + (size_t)m * D) + lane;
; #pragma unroll
;                 for (int j = 0; j < 4; ++j) xs[64 * j] = xv[j];
;             }
;             if (HAS_XN) {
;                 float ss = 0.f;
; #pragma unroll
	v_add_f32_e32 v51, v51, v85
	v_fmamk_f32 v51, v51, 0x3a800000, v77
	v_mul_f32_e32 v85, 0x4f800000, v51
	v_cmp_gt_f32_e32 vcc, s12, v51
	s_nop 1
	v_cndmask_b32_e32 v51, v51, v85, vcc
	v_sqrt_f32_e32 v85, v51
	s_nop 0
	v_add_u32_e32 v102, -1, v85
	v_add_u32_e32 v103, 1, v85
	v_fma_f32 v104, -v102, v85, v51
	v_fma_f32 v105, -v103, v85, v51
	v_cmp_ge_f32_e64 s[6:7], 0, v104
	s_nop 1
	v_cndmask_b32_e64 v85, v85, v102, s[6:7]
	v_cmp_lt_f32_e64 s[6:7], 0, v105
	s_nop 1
	v_cndmask_b32_e64 v85, v85, v103, s[6:7]
	v_mul_f32_e32 v102, 0x37800000, v85
	v_cndmask_b32_e32 v85, v85, v102, vcc
	v_cmp_class_f32_e32 vcc, v51, v78
	s_nop 1
	v_cndmask_b32_e32 v51, v85, v51, vcc
	v_div_scale_f32 v85, s[6:7], v51, v51, 1.0
	v_rcp_f32_e32 v103, v85
	v_div_scale_f32 v102, vcc, 1.0, v51, 1.0
	v_fma_f32 v104, -v85, v103, 1.0
	v_fmac_f32_e32 v103, v104, v103
	v_mul_f32_e32 v104, v102, v103
	v_fma_f32 v105, -v85, v104, v102
	v_fmac_f32_e32 v104, v105, v103
	v_fma_f32 v85, -v85, v104, v102
	v_div_fmas_f32 v85, v85, v103, v104
	v_div_fixup_f32 v102, v85, v51, 1.0
	v_pk_mul_f32 v[38:39], v[38:39], v[102:103] op_sel_hi:[1,0]
	v_pk_mul_f32 v[36:37], v[36:37], v[102:103] op_sel_hi:[1,0]
	v_pk_mul_f32 v[34:35], v[34:35], v[102:103] op_sel_hi:[1,0]
	v_pk_mul_f32 v[32:33], v[32:33], v[102:103] op_sel_hi:[1,0]
	v_pk_mul_f32 v[46:47], v[46:47], v[102:103] op_sel_hi:[1,0]
	v_pk_mul_f32 v[44:45], v[44:45], v[102:103] op_sel_hi:[1,0]
	v_pk_mul_f32 v[42:43], v[42:43], v[102:103] op_sel_hi:[1,0]
	v_pk_mul_f32 v[40:41], v[40:41], v[102:103] op_sel_hi:[1,0]
	v_pk_mul_f32 v[36:37], v[0:1], v[36:37]
	v_pk_mul_f32 v[38:39], v[2:3], v[38:39]
	v_pk_mul_f32 v[32:33], v[12:13], v[32:33]
	v_pk_mul_f32 v[34:35], v[14:15], v[34:35]
	v_pk_mul_f32 v[44:45], v[4:5], v[44:45]
	v_pk_mul_f32 v[46:47], v[6:7], v[46:47]
	v_pk_mul_f32 v[40:41], v[8:9], v[40:41]
	v_pk_mul_f32 v[42:43], v[10:11], v[42:43]
	v_pk_fma_f32 v[38:39], v[60:61], v[38:39], v[18:19]
	v_pk_fma_f32 v[36:37], v[62:63], v[36:37], v[16:17]
	v_pk_fma_f32 v[34:35], v[72:73], v[34:35], v[30:31]
	v_pk_fma_f32 v[32:33], v[74:75], v[32:33], v[28:29]
	v_pk_fma_f32 v[46:47], v[64:65], v[46:47], v[22:23]
	v_pk_fma_f32 v[44:45], v[66:67], v[44:45], v[20:21]
	v_pk_fma_f32 v[42:43], v[68:69], v[42:43], v[26:27]
	v_pk_fma_f32 v[40:41], v[70:71], v[40:41], v[24:25]
	v_cvt_pk_f16_f32 v36, v36, v37
	v_cvt_pk_f16_f32 v37, v38, v39
	v_cvt_pk_f16_f32 v32, v32, v33
	v_cvt_pk_f16_f32 v33, v34, v35
	v_cvt_pk_f16_f32 v38, v44, v45
	v_cvt_pk_f16_f32 v39, v46, v47
	v_cvt_pk_f16_f32 v40, v40, v41
	v_cvt_pk_f16_f32 v41, v42, v43
	global_store_dwordx2 v[58:59], v[36:37], off
	global_store_dwordx2 v[58:59], v[38:39], off offset:512
	global_store_dwordx2 v[58:59], v[40:41], off offset:1024
	global_store_dwordx2 v[58:59], v[32:33], off offset:1536
	s_waitcnt vmcnt(0)
	v_mov_b64_e32 v[32:33], v[94:95]
	v_lshl_add_u64 v[58:59], v[58:59], 0, s[10:11]
	v_mov_b64_e32 v[34:35], v[96:97]
	v_mov_b32_e32 v36, v86
	v_mov_b32_e32 v37, v87
	v_mov_b32_e32 v38, v88
	v_mov_b32_e32 v39, v89
	v_mov_b32_e32 v44, v90
	v_mov_b32_e32 v45, v91
	v_mov_b32_e32 v46, v92
	v_mov_b32_e32 v47, v93
	v_mov_b32_e32 v40, v98
	v_mov_b32_e32 v41, v99
	v_mov_b32_e32 v42, v100
	v_mov_b32_e32 v43, v101
	v_mov_b32_e32 v86, v94
	v_mov_b32_e32 v87, v95
	v_mov_b32_e32 v51, v96
	v_mov_b32_e32 v85, v97
	s_mov_b64 vcc, s[4:5]
	s_cbranch_vccnz .LBB0_111
	global_load_dwordx4 v[0:3], v[56:57], off
	global_load_dwordx4 v[4:7], v[56:57], off offset:1024
	global_load_dwordx4 v[8:11], v[56:57], off offset:2048
	global_load_dwordx4 v[12:15], v[56:57], off offset:3072
.LBB0_113:
	s_andn2_b64 vcc, exec, s[8:9]
	s_cbranch_vccnz .LBB0_116
	v_add_co_u32_e32 v24, vcc, 0x6000, v54
	s_addk_i32 s2, 0x4000
	s_nop 0
	v_addc_co_u32_e32 v25, vcc, 0, v55, vcc
	v_add_co_u32_e32 v52, vcc, 0x6000, v52
	s_ashr_i32 s3, s2, 31
	s_nop 0
	v_addc_co_u32_e32 v53, vcc, 0, v53, vcc
	global_load_dwordx4 v[54:57], v[24:25], off
	global_load_dwordx4 v[58:61], v[24:25], off offset:1024
	global_load_dwordx4 v[16:19], v[52:53], off
	global_load_dwordx4 v[20:23], v[52:53], off offset:1024
	global_load_dwordx4 v[62:65], v[24:25], off offset:2048
	global_load_dwordx4 v[78:81], v[24:25], off offset:3072
	s_lshl_b64 s[4:5], s[2:3], 12
	v_lshl_add_u64 v[66:67], v[48:49], 0, s[4:5]
	global_load_dwordx4 v[40:43], v[66:67], off offset:2048
	global_load_dwordx4 v[32:35], v[66:67], off offset:3072
	global_load_dwordx4 v[24:27], v[52:53], off offset:2048
	global_load_dwordx4 v[28:31], v[52:53], off offset:3072
	global_load_dwordx4 v[36:39], v[66:67], off
	global_load_dwordx4 v[44:47], v[66:67], off offset:1024
	v_mbcnt_hi_u32_b32 v52, -1, v76
	v_and_b32_e32 v53, 64, v52
	v_xor_b32_e32 v66, 1, v52
	v_add_u32_e32 v53, 64, v53
	v_xor_b32_e32 v67, 2, v52
	v_cmp_lt_i32_e32 vcc, v66, v53
	v_xor_b32_e32 v70, 4, v52
	v_xor_b32_e32 v71, 8, v52
	v_cndmask_b32_e32 v66, v52, v66, vcc
	v_cmp_lt_i32_e32 vcc, v67, v53
	v_xor_b32_e32 v72, 16, v52
	s_lshl_b64 s[6:7], s[2:3], 11
	v_cndmask_b32_e32 v67, v52, v67, vcc
	v_cmp_lt_i32_e32 vcc, v70, v53
	v_xor_b32_e32 v73, 32, v52
	s_add_u32 s0, s0, s6
	v_cndmask_b32_e32 v74, v52, v70, vcc
	v_cmp_lt_i32_e32 vcc, v71, v53
	v_mov_b32_e32 v51, 0
	s_addc_u32 s1, s1, s7
	v_cndmask_b32_e32 v75, v52, v71, vcc
	v_cmp_lt_i32_e32 vcc, v72, v53
	s_mov_b64 s[4:5], 0x4800000
	s_ashr_i32 s81, s80, 31
	v_cndmask_b32_e32 v77, v52, v72, vcc
	v_cmp_lt_i32_e32 vcc, v73, v53
	v_lshl_add_u64 v[50:51], s[0:1], 0, v[50:51]
	v_mov_b32_e32 v68, 0x358637bd
	v_cndmask_b32_e32 v52, v52, v73, vcc
	s_mov_b32 s8, 0xf800000
	v_mov_b32_e32 v69, 0x260
	v_lshlrev_b32_e32 v70, 2, v66
	v_lshlrev_b32_e32 v71, 2, v67
	v_lshlrev_b32_e32 v72, 2, v74
	v_lshlrev_b32_e32 v73, 2, v75
	v_lshlrev_b32_e32 v74, 2, v77
	v_lshlrev_b32_e32 v75, 2, v52
	s_lshl_b64 s[0:1], s[80:81], 11
	v_lshl_add_u64 v[50:51], v[50:51], 0, s[4:5]
	s_waitcnt vmcnt(0) lgkmcnt(0)
	v_pk_add_f32 v[52:53], v[56:57], 1.0 op_sel_hi:[1,0]
	v_pk_add_f32 v[54:55], v[54:55], 1.0 op_sel_hi:[1,0]
	v_pk_add_f32 v[56:57], v[60:61], 1.0 op_sel_hi:[1,0]
	v_pk_add_f32 v[58:59], v[58:59], 1.0 op_sel_hi:[1,0]
	v_pk_add_f32 v[60:61], v[64:65], 1.0 op_sel_hi:[1,0]
	v_pk_add_f32 v[62:63], v[62:63], 1.0 op_sel_hi:[1,0]
	v_pk_add_f32 v[64:65], v[80:81], 1.0 op_sel_hi:[1,0]
	v_pk_add_f32 v[66:67], v[78:79], 1.0 op_sel_hi:[1,0]
	v_mov_b32_e32 v79, v32
	v_mov_b32_e32 v80, v33
	v_mov_b32_e32 v77, v34
	v_mov_b32_e32 v78, v35
; template <bool HAS_H, bool HAS_XN, int XL, int XS>
; __device__ __forceinline__ void rowwise_phase(const float* xf, half_t* x16, float* xo, const half_t* hs, const float* nwA, const float* gvec, const float* nwB, const float* scv, const float* shv, half_t* xn, int gw, int NW, int lane) {
;     ...
;         for (int m = b * S + gw; m < mend; m += NW) {
;             f32x4 xv[4]; half4 hcur[4];
; #pragma unroll
;             for (int j = 0; j < 4; ++j) { if (XL == 0) xv[j] = xq[j]; else xv[j] = (f32x4){(float)xh[j][0], (float)xh[j][1], (float)xh[j][2], (float)xh[j][3]}; if (HAS_H) hcur[j] = hq[j]; }
;             const int mn = (m + NW < mend) ? m + NW : m;
;             {
;                 if (XL == 0) { const f32x4* xr = (const f32x4*)(xf + (size_t)mn * D) + lane;
; #pragma unroll
;                     for (int j = 0; j < 4; ++j) xq[j] = xr[64 * j]; }
;                 else { const half4* xr = (const half4*)(x16 + (size_t)mn * D) + lane;
; #pragma unroll
;                     for (int j = 0; j < 4; ++j) xh[j] = xr[64 * j]; }
;                 if (HAS_H) { const half4* hr = (const half4*)(hs + (size_t)mn * D) + lane;
; #pragma unroll
;                     for (int j = 0; j < 4; ++j) hq[j] = hr[64 * j]; }
;             }
;             if (HAS_H) {
;                 f32x4 hv[4]; float ss = 0.f;
; #pragma unroll
;                 for (int j = 0; j < 4; ++j) { const half4 h4 = hcur[j]; hv[j] = (f32x4){(float)h4[0], (float)h4[1], (float)h4[2], (float)h4[3]}; ss += (hv[j][0] * hv[j][0] + hv[j][1] * hv[j][1]) + (hv[j][2] * hv[j][2] + hv[j][3] * hv[j][3]); }
;                 const float r = 1.0f / sqrtf(wave_sum(ss) * (1.f / D) + RMS_EPS);
; #pragma unroll
;                 for (int j = 0; j < 4; ++j) xv[j] = xv[j] + gg[j] * (hv[j] * r * wA[j]);
;             }
;             if (XS == 1) {
;                 u32x2* xs = (u32x2*)(x16 + (size_t)m * D) + lane;
; #pragma unroll
;                 for (int j = 0; j < 4; ++j) { u32x2 pk; pk.x = pg8::pkh(xv[j][0], xv[j][1]); pk.y = pg8::pkh(xv[j][2], xv[j][3]); xs[64 * j] = pk; }
;             } else if (XS == 2) {
;                 f32x4* xs = (f32x4*)(xo + (size_t)m * D) + lane;
; #pragma unroll
;                 for (int j = 0; j < 4; ++j) xs[64 * j] = xv[j];
;             }
;             if (HAS_XN) {
;                 float ss = 0.f;
; #pragma unroll
.LBB0_115:
	s_add_i32 s3, s2, s80
	v_pk_mul_f32 v[82:83], v[46:47], v[46:47]
	v_pk_mul_f32 v[84:85], v[44:45], v[44:45]
	v_pk_mul_f32 v[86:87], v[38:39], v[38:39]
	v_pk_mul_f32 v[88:89], v[36:37], v[36:37]
	s_cmp_lt_i32 s3, 0x8000
	v_mul_f32_e32 v90, v40, v40
	v_mul_f32_e32 v92, v42, v42
	v_pk_mov_b32 v[94:95], v[88:89], v[86:87] op_sel:[1,0]
	v_mov_b32_e32 v89, v87
	v_pk_mov_b32 v[86:87], v[84:85], v[82:83] op_sel:[1,0]
	v_mov_b32_e32 v85, v83
	s_cselect_b64 s[4:5], -1, 0
	v_pk_fma_f32 v[82:83], v[40:41], v[40:41], v[90:91] op_sel_hi:[1,1,0]
	v_pk_fma_f32 v[90:91], v[42:43], v[42:43], v[92:93] op_sel_hi:[1,1,0]
	v_pk_add_f32 v[88:89], v[94:95], v[88:89]
	v_pk_add_f32 v[84:85], v[86:87], v[84:85]
	s_and_b64 s[4:5], s[4:5], exec
	v_mul_f32_e32 v90, v80, v80
	v_pk_add_f32 v[80:81], v[88:89], v[88:89] op_sel_hi:[0,1]
	v_pk_add_f32 v[84:85], v[84:85], v[84:85] op_sel_hi:[0,1]
	s_cselect_b32 s6, s3, s2
	v_mul_f32_e32 v82, v79, v79
	v_mul_f32_e32 v80, v77, v77
	v_mul_f32_e32 v84, v78, v78
	s_ashr_i32 s7, s6, 31
	v_pk_add_f32 v[82:83], v[82:83], v[90:91]
	v_pk_add_f32 v[78:79], v[80:81], v[84:85]
	s_lshl_b64 s[6:7], s[6:7], 12
	v_pk_add_f32 v[78:79], v[82:83], v[78:79]
	v_lshl_add_u64 v[94:95], v[48:49], 0, s[6:7]
	v_add_f32_e32 v77, v78, v79
	global_load_dwordx4 v[78:81], v[94:95], off
	global_load_dwordx4 v[82:85], v[94:95], off offset:1024
	global_load_dwordx4 v[86:89], v[94:95], off offset:2048
	global_load_dwordx4 v[90:93], v[94:95], off offset:3072
	ds_bpermute_b32 v96, v70, v77
	s_mov_b32 s2, s3
	s_waitcnt lgkmcnt(0)
	v_add_f32_e32 v77, v77, v96
	ds_bpermute_b32 v94, v71, v77
	s_waitcnt lgkmcnt(0)
	v_add_f32_e32 v77, v77, v94
	ds_bpermute_b32 v94, v72, v77
	s_waitcnt lgkmcnt(0)
	v_add_f32_e32 v77, v77, v94
	ds_bpermute_b32 v94, v73, v77
	s_waitcnt lgkmcnt(0)
	v_add_f32_e32 v77, v77, v94
	ds_bpermute_b32 v94, v74, v77
	s_waitcnt lgkmcnt(0)
	v_add_f32_e32 v77, v77, v94
	ds_bpermute_b32 v94, v75, v77
	s_waitcnt lgkmcnt(0)
	v_add_f32_e32 v77, v77, v94
	v_fmamk_f32 v77, v77, 0x3a800000, v68
	v_mul_f32_e32 v94, 0x4f800000, v77
	v_cmp_gt_f32_e32 vcc, s8, v77
	s_nop 1
	v_cndmask_b32_e32 v77, v77, v94, vcc
	v_sqrt_f32_e32 v94, v77
	s_nop 0
	v_add_u32_e32 v95, -1, v94
	v_add_u32_e32 v96, 1, v94
	v_fma_f32 v97, -v95, v94, v77
	v_fma_f32 v98, -v96, v94, v77
	v_cmp_ge_f32_e64 s[6:7], 0, v97
	s_nop 1
	v_cndmask_b32_e64 v94, v94, v95, s[6:7]
	v_cmp_lt_f32_e64 s[6:7], 0, v98
	s_nop 1
	v_cndmask_b32_e64 v94, v94, v96, s[6:7]
	v_mul_f32_e32 v95, 0x37800000, v94
	v_cndmask_b32_e32 v94, v94, v95, vcc
	v_cmp_class_f32_e32 vcc, v77, v69
	s_nop 1
	v_cndmask_b32_e32 v77, v94, v77, vcc
	v_div_scale_f32 v94, s[6:7], v77, v77, 1.0
	v_rcp_f32_e32 v96, v94
	v_div_scale_f32 v95, vcc, 1.0, v77, 1.0
	v_fma_f32 v97, -v94, v96, 1.0
	v_fmac_f32_e32 v96, v97, v96
	v_mul_f32_e32 v97, v95, v96
	v_fma_f32 v98, -v94, v97, v95
	v_fmac_f32_e32 v97, v98, v96
	v_fma_f32 v94, -v94, v97, v95
	v_div_fmas_f32 v94, v94, v96, v97
	v_div_fixup_f32 v94, v94, v77, 1.0
	v_pk_mul_f32 v[38:39], v[38:39], v[94:95] op_sel_hi:[1,0]
	v_pk_mul_f32 v[36:37], v[36:37], v[94:95] op_sel_hi:[1,0]
	v_pk_mul_f32 v[34:35], v[34:35], v[94:95] op_sel_hi:[1,0]
	v_pk_mul_f32 v[32:33], v[32:33], v[94:95] op_sel_hi:[1,0]
	v_pk_mul_f32 v[46:47], v[46:47], v[94:95] op_sel_hi:[1,0]
	v_pk_mul_f32 v[44:45], v[44:45], v[94:95] op_sel_hi:[1,0]
	v_pk_mul_f32 v[42:43], v[42:43], v[94:95] op_sel_hi:[1,0]
	v_pk_mul_f32 v[40:41], v[40:41], v[94:95] op_sel_hi:[1,0]
	v_pk_mul_f32 v[36:37], v[0:1], v[36:37]
	v_pk_mul_f32 v[38:39], v[2:3], v[38:39]
	v_pk_mul_f32 v[32:33], v[12:13], v[32:33]
	v_pk_mul_f32 v[34:35], v[14:15], v[34:35]
	v_pk_mul_f32 v[44:45], v[4:5], v[44:45]
	v_pk_mul_f32 v[46:47], v[6:7], v[46:47]
	v_pk_mul_f32 v[40:41], v[8:9], v[40:41]
	v_pk_mul_f32 v[42:43], v[10:11], v[42:43]
	v_pk_fma_f32 v[38:39], v[52:53], v[38:39], v[18:19]
	v_pk_fma_f32 v[36:37], v[54:55], v[36:37], v[16:17]
	v_pk_fma_f32 v[34:35], v[64:65], v[34:35], v[30:31]
	v_pk_fma_f32 v[32:33], v[66:67], v[32:33], v[28:29]
	v_pk_fma_f32 v[46:47], v[56:57], v[46:47], v[22:23]
	v_pk_fma_f32 v[44:45], v[58:59], v[44:45], v[20:21]
	v_pk_fma_f32 v[42:43], v[60:61], v[42:43], v[26:27]
	v_pk_fma_f32 v[40:41], v[62:63], v[40:41], v[24:25]
	v_cvt_pk_f16_f32 v36, v36, v37
	v_cvt_pk_f16_f32 v37, v38, v39
	v_cvt_pk_f16_f32 v32, v32, v33
	v_cvt_pk_f16_f32 v33, v34, v35
	v_cvt_pk_f16_f32 v38, v44, v45
	v_cvt_pk_f16_f32 v39, v46, v47
	v_cvt_pk_f16_f32 v40, v40, v41
	v_cvt_pk_f16_f32 v41, v42, v43
	global_store_dwordx2 v[50:51], v[36:37], off
	global_store_dwordx2 v[50:51], v[38:39], off offset:512
	global_store_dwordx2 v[50:51], v[40:41], off offset:1024
	global_store_dwordx2 v[50:51], v[32:33], off offset:1536
	s_waitcnt vmcnt(0)
	v_mov_b64_e32 v[32:33], v[90:91]
	v_lshl_add_u64 v[50:51], v[50:51], 0, s[0:1]
	v_mov_b64_e32 v[34:35], v[92:93]
	v_mov_b32_e32 v36, v78
	v_mov_b32_e32 v37, v79
	v_mov_b32_e32 v38, v80
	v_mov_b32_e32 v39, v81
	v_mov_b32_e32 v44, v82
	v_mov_b32_e32 v45, v83
	v_mov_b32_e32 v46, v84
	v_mov_b32_e32 v47, v85
	v_mov_b32_e32 v40, v86
	v_mov_b32_e32 v41, v87
	v_mov_b32_e32 v42, v88
	v_mov_b32_e32 v43, v89
	v_mov_b32_e32 v79, v90
	v_mov_b32_e32 v80, v91
	v_mov_b32_e32 v77, v92
	v_mov_b32_e32 v78, v93
	s_mov_b64 vcc, s[4:5]
	s_cbranch_vccnz .LBB0_115

; template <bool HAS_H, bool HAS_XN, int XL, int XS>
; __device__ __forceinline__ void rowwise_phase(const float* xf, half_t* x16, float* xo, const half_t* hs, const float* nwA, const float* gvec, const float* nwB, const float* scv, const float* shv, half_t* xn, int gw, int NW, int lane) {
;     ...
;         f32x4 wA[4], gg[4], wB[4], sc1[4], sh[4];
; #pragma unroll
;         for (int j = 0; j < 4; ++j) {
;             if (HAS_H) { wA[j] = *((const f32x4*)nwA + lane + 64 * j); gg[j] = *((const f32x4*)(gvec + (size_t)b * 6144) + lane + 64 * j); }
;             if (HAS_XN) { wB[j] = *((const f32x4*)nwB + lane + 64 * j); sc1[j] = *((const f32x4*)(scv + (size_t)b * 6144) + lane + 64 * j) + 1.0f; sh[j] = *((const f32x4*)(shv + (size_t)b * 6144) + lane + 64 * j); }
;         }
;         const int mend = (b + 1) * S;
;         f32x4 xq[4]; half4 xh[4], hq[4];
;         {
;             const int m0 = b * S + gw;
;             if (m0 < mend) {
;                 if (XL == 0) { const f32x4* xr = (const f32x4*)(xf + (size_t)m0 * D) + lane;
; #pragma unroll
;                     for (int j = 0; j < 4; ++j) xq[j] = xr[64 * j]; }
;                 else { const half4* xr = (const half4*)(x16 + (size_t)m0 * D) + lane;
; #pragma unroll
;                     for (int j = 0; j < 4; ++j) xh[j] = xr[64 * j]; }
;                 if (HAS_H) { const half4* hr = (const half4*)(hs + (size_t)m0 * D) + lane;
; #pragma unroll
;                     for (int j = 0; j < 4; ++j) hq[j] = hr[64 * j]; }
;             }
.LBB0_1230:
	s_mul_i32 s84, s4, 0x1800
	s_lshl_b64 s[2:3], s[84:85], 2
	s_waitcnt vmcnt(0) lgkmcnt(0)
	v_lshl_add_u64 v[46:47], v[86:87], 0, s[2:3]
	v_lshl_add_u64 v[58:59], v[90:91], 0, s[2:3]
	v_lshl_add_u64 v[62:63], v[92:93], 0, s[2:3]
	global_load_dwordx4 v[2:5], v[84:85], off
	global_load_dwordx4 v[6:9], v[84:85], off offset:1024
	global_load_dwordx4 v[10:13], v[46:47], off
	global_load_dwordx4 v[14:17], v[46:47], off offset:1024
	global_load_dwordx4 v[18:21], v[88:89], off
	global_load_dwordx4 v[22:25], v[88:89], off offset:1024
	global_load_dwordx4 v[78:81], v[58:59], off
	global_load_dwordx4 v[70:73], v[58:59], off offset:1024
	global_load_dwordx4 v[26:29], v[62:63], off
	global_load_dwordx4 v[30:33], v[62:63], off offset:1024
	global_load_dwordx4 v[34:37], v[84:85], off offset:2048
	global_load_dwordx4 v[38:41], v[84:85], off offset:3072
	global_load_dwordx4 v[42:45], v[46:47], off offset:2048
	s_nop 0
	global_load_dwordx4 v[46:49], v[46:47], off offset:3072
	s_nop 0
	global_load_dwordx4 v[50:53], v[88:89], off offset:2048
	global_load_dwordx4 v[54:57], v[88:89], off offset:3072
	global_load_dwordx4 v[74:77], v[58:59], off offset:2048
	global_load_dwordx4 v[66:69], v[58:59], off offset:3072
	s_nop 0
	global_load_dwordx4 v[58:61], v[62:63], off offset:2048
	s_nop 0
	global_load_dwordx4 v[62:65], v[62:63], off offset:3072
	s_lshl_b32 s2, s4, 14
	v_cndmask_b32_e64 v83, 0, 1, s[16:17]
	v_cmp_ne_u32_e64 s[4:5], 1, v83
	s_andn2_b64 vcc, exec, s[16:17]
	s_add_i32 s20, s2, s22
	s_cbranch_vccnz .LBB0_1232
	s_ashr_i32 s21, s20, 31
	s_lshl_b64 s[24:25], s[20:21], 11
	v_lshl_add_u64 v[100:101], v[94:95], 0, s[24:25]
	v_lshl_add_u64 v[106:107], v[96:97], 0, s[24:25]
	global_load_dwordx2 v[102:103], v[100:101], off
	global_load_dwordx2 v[104:105], v[100:101], off offset:512
	global_load_dwordx2 v[98:99], v[100:101], off offset:1024
	s_nop 0
	global_load_dwordx2 v[100:101], v[100:101], off offset:1536
	s_nop 0
	global_load_dwordx2 v[114:115], v[106:107], off
	global_load_dwordx2 v[112:113], v[106:107], off offset:512
	global_load_dwordx2 v[110:111], v[106:107], off offset:1024
	global_load_dwordx2 v[108:109], v[106:107], off offset:1536
	s_waitcnt vmcnt(0) lgkmcnt(0)
	v_mov_b32_e32 v143, v101

; template <bool HAS_H, bool HAS_XN, int XL, int XS>
; __device__ __forceinline__ void rowwise_phase(const float* xf, half_t* x16, float* xo, const half_t* hs, const float* nwA, const float* gvec, const float* nwB, const float* scv, const float* shv, half_t* xn, int gw, int NW, int lane) {
;     ...
;             f32x4 xv[4]; half4 hcur[4];
; #pragma unroll
;             for (int j = 0; j < 4; ++j) { if (XL == 0) xv[j] = xq[j]; else xv[j] = (f32x4){(float)xh[j][0], (float)xh[j][1], (float)xh[j][2], (float)xh[j][3]}; if (HAS_H) hcur[j] = hq[j]; }
;             const int mn = (m + NW < mend) ? m + NW : m;
;             {
;                 if (XL == 0) { const f32x4* xr = (const f32x4*)(xf + (size_t)mn * D) + lane;
; #pragma unroll
;                     for (int j = 0; j < 4; ++j) xq[j] = xr[64 * j]; }
;                 else { const half4* xr = (const half4*)(x16 + (size_t)mn * D) + lane;
; #pragma unroll
;                     for (int j = 0; j < 4; ++j) xh[j] = xr[64 * j]; }
;                 if (HAS_H) { const half4* hr = (const half4*)(hs + (size_t)mn * D) + lane;
; #pragma unroll
;                     for (int j = 0; j < 4; ++j) hq[j] = hr[64 * j]; }
;             }
;             if (HAS_H) {
;                 f32x4 hv[4]; float ss = 0.f;
; #pragma unroll
;                 for (int j = 0; j < 4; ++j) { const half4 h4 = hcur[j]; hv[j] = (f32x4){(float)h4[0], (float)h4[1], (float)h4[2], (float)h4[3]}; ss += (hv[j][0] * hv[j][0] + hv[j][1] * hv[j][1]) + (hv[j][2] * hv[j][2] + hv[j][3] * hv[j][3]); }
;                 const float r = 1.0f / sqrtf(wave_sum(ss) * (1.f / D) + RMS_EPS);
; #pragma unroll
;                 for (int j = 0; j < 4; ++j) xv[j] = xv[j] + gg[j] * (hv[j] * r * wA[j]);
.LBB0_1234:
	v_cvt_f32_f16_sdwa v147, v114 dst_sel:DWORD dst_unused:UNUSED_PAD src0_sel:WORD_1
	v_cvt_f32_f16_sdwa v149, v115 dst_sel:DWORD dst_unused:UNUSED_PAD src0_sel:WORD_1
	v_cvt_f32_f16_e32 v146, v114
	v_cvt_f32_f16_e32 v148, v115
	v_mov_b32_e32 v150, v147
	v_mov_b32_e32 v151, v149
	v_mov_b32_e32 v114, v146
	v_mov_b32_e32 v115, v148
	v_pk_mul_f32 v[150:151], v[150:151], v[150:151]
	v_cvt_f32_f16_sdwa v153, v113 dst_sel:DWORD dst_unused:UNUSED_PAD src0_sel:WORD_1
	v_pk_fma_f32 v[114:115], v[114:115], v[114:115], v[150:151]
	v_cvt_f32_f16_sdwa v151, v112 dst_sel:DWORD dst_unused:UNUSED_PAD src0_sel:WORD_1
	v_cvt_f32_f16_e32 v150, v112
	v_cvt_f32_f16_e32 v152, v113
	v_mov_b32_e32 v155, v153
	v_mov_b32_e32 v154, v151
	v_mov_b32_e32 v112, v150
	v_mov_b32_e32 v113, v152
	v_pk_mul_f32 v[154:155], v[154:155], v[154:155]
	v_cvt_f32_f16_e32 v156, v111
	v_pk_fma_f32 v[112:113], v[112:113], v[112:113], v[154:155]
	v_cvt_f32_f16_e32 v154, v110
	v_cvt_f32_f16_sdwa v155, v110 dst_sel:DWORD dst_unused:UNUSED_PAD src0_sel:WORD_1
	v_cvt_f32_f16_sdwa v157, v111 dst_sel:DWORD dst_unused:UNUSED_PAD src0_sel:WORD_1
	v_cvt_f32_f16_sdwa v161, v108 dst_sel:DWORD dst_unused:UNUSED_PAD src0_sel:WORD_1
	v_cvt_f32_f16_e32 v160, v108
	v_cvt_f32_f16_sdwa v163, v109 dst_sel:DWORD dst_unused:UNUSED_PAD src0_sel:WORD_1
	v_cvt_f32_f16_e32 v162, v109
	v_mul_f32_e32 v110, v154, v154
	v_pk_fma_f32 v[110:111], v[154:155], v[154:155], v[110:111] op_sel_hi:[1,1,0]
	v_pk_add_f32 v[114:115], v[114:115], v[114:115] op_sel_hi:[0,1]
	v_mul_f32_e32 v110, v156, v156
	v_pk_add_f32 v[112:113], v[112:113], v[112:113] op_sel_hi:[0,1]
	v_pk_fma_f32 v[158:159], v[156:157], v[156:157], v[110:111] op_sel_hi:[1,1,0]
	v_pk_mul_f32 v[108:109], v[160:161], v[160:161]
	v_pk_mul_f32 v[164:165], v[162:163], v[162:163]
	v_mov_b32_e32 v110, v108
	v_mov_b32_e32 v158, v109
	v_mov_b32_e32 v114, v164
	v_mov_b32_e32 v112, v165
	v_pk_add_f32 v[108:109], v[110:111], v[158:159]
	v_pk_add_f32 v[110:111], v[114:115], v[112:113]
	s_add_i32 s3, s20, s80
	v_pk_add_f32 v[108:109], v[108:109], v[110:111]
	s_cmp_lt_i32 s3, s2
	v_add_f32_e32 v108, v108, v109
	ds_bpermute_b32 v109, v83, v108
	s_cselect_b32 s4, s3, s20
	s_ashr_i32 s5, s4, 31
	s_lshl_b64 s[4:5], s[4:5], 11
	v_cvt_f32_f16_sdwa v133, v100 dst_sel:DWORD dst_unused:UNUSED_PAD src0_sel:WORD_1
	s_waitcnt lgkmcnt(0)
	v_add_f32_e32 v108, v108, v109
	ds_bpermute_b32 v109, v138, v108
	v_cvt_f32_f16_e32 v132, v100
	v_lshl_add_u64 v[100:101], v[94:95], 0, s[4:5]
	v_lshl_add_u64 v[116:117], v[96:97], 0, s[4:5]
	v_cvt_f32_f16_sdwa v127, v103 dst_sel:DWORD dst_unused:UNUSED_PAD src0_sel:WORD_1
	s_waitcnt lgkmcnt(0)
	v_add_f32_e32 v108, v108, v109
	ds_bpermute_b32 v109, v139, v108
	v_cvt_f32_f16_e32 v126, v103
	v_cvt_f32_f16_sdwa v125, v102 dst_sel:DWORD dst_unused:UNUSED_PAD src0_sel:WORD_1
	v_cvt_f32_f16_e32 v124, v102
	v_cvt_f32_f16_sdwa v135, v105 dst_sel:DWORD dst_unused:UNUSED_PAD src0_sel:WORD_1
	s_waitcnt lgkmcnt(0)
	v_add_f32_e32 v108, v108, v109
	ds_bpermute_b32 v109, v140, v108
	v_cvt_f32_f16_e32 v134, v105
	v_cvt_f32_f16_sdwa v129, v104 dst_sel:DWORD dst_unused:UNUSED_PAD src0_sel:WORD_1
	v_cvt_f32_f16_e32 v128, v104
	v_cvt_f32_f16_sdwa v137, v99 dst_sel:DWORD dst_unused:UNUSED_PAD src0_sel:WORD_1
	s_waitcnt lgkmcnt(0)
	v_add_f32_e32 v108, v108, v109
	ds_bpermute_b32 v109, v141, v108
	v_cvt_f32_f16_e32 v136, v99
	v_cvt_f32_f16_sdwa v131, v98 dst_sel:DWORD dst_unused:UNUSED_PAD src0_sel:WORD_1
	v_cvt_f32_f16_e32 v130, v98
	v_cvt_f32_f16_sdwa v145, v143 dst_sel:DWORD dst_unused:UNUSED_PAD src0_sel:WORD_1
	s_waitcnt lgkmcnt(0)
	v_add_f32_e32 v108, v108, v109
	ds_bpermute_b32 v109, v142, v108
	v_cvt_f32_f16_e32 v144, v143
	global_load_dwordx2 v[102:103], v[100:101], off
	global_load_dwordx2 v[104:105], v[100:101], off offset:512
	global_load_dwordx2 v[98:99], v[100:101], off offset:1024
	s_nop 0
	global_load_dwordx2 v[100:101], v[100:101], off offset:1536
	s_nop 0
	global_load_dwordx2 v[122:123], v[116:117], off
	global_load_dwordx2 v[120:121], v[116:117], off offset:512
	global_load_dwordx2 v[118:119], v[116:117], off offset:1024
	s_nop 0
	global_load_dwordx2 v[116:117], v[116:117], off offset:1536
	s_cmp_ge_i32 s3, s2
	s_waitcnt lgkmcnt(0)
	v_add_f32_e32 v108, v108, v109
	v_fmamk_f32 v108, v108, 0x3a800000, v201
	v_cmp_gt_f32_e32 vcc, s81, v108
	v_mul_f32_e32 v109, 0x4f800000, v108
	s_mov_b32 s20, s3
	v_cndmask_b32_e32 v108, v108, v109, vcc
	v_sqrt_f32_e32 v109, v108
	s_nop 0
	v_add_u32_e32 v110, -1, v109
	v_fma_f32 v111, -v110, v109, v108
	v_cmp_ge_f32_e64 s[4:5], 0, v111
	v_add_u32_e32 v111, 1, v109
	s_nop 0
	v_cndmask_b32_e64 v110, v109, v110, s[4:5]
	v_fma_f32 v109, -v111, v109, v108
	v_cmp_lt_f32_e64 s[4:5], 0, v109
	s_nop 1
	v_cndmask_b32_e64 v109, v110, v111, s[4:5]
	v_mul_f32_e32 v110, 0x37800000, v109
	v_cndmask_b32_e32 v109, v109, v110, vcc
	v_cmp_class_f32_e32 vcc, v108, v202
	s_nop 1
	v_cndmask_b32_e32 v108, v109, v108, vcc
	v_div_scale_f32 v109, s[4:5], v108, v108, 1.0
	v_rcp_f32_e32 v110, v109
	s_nop 0
	v_fma_f32 v111, -v109, v110, 1.0
	v_fmac_f32_e32 v110, v111, v110
	v_div_scale_f32 v111, vcc, 1.0, v108, 1.0
	v_mul_f32_e32 v112, v111, v110
	v_fma_f32 v113, -v109, v112, v111
	v_fmac_f32_e32 v112, v113, v110
	v_fma_f32 v109, -v109, v112, v111
	v_div_fmas_f32 v109, v109, v110, v112
	v_div_fixup_f32 v108, v109, v108, 1.0
	v_pk_mul_f32 v[110:111], v[148:149], v[108:109] op_sel_hi:[1,0]
	v_pk_mul_f32 v[112:113], v[146:147], v[108:109] op_sel_hi:[1,0]
	v_pk_mul_f32 v[110:111], v[4:5], v[110:111]
	v_pk_mul_f32 v[112:113], v[2:3], v[112:113]
	v_pk_fma_f32 v[146:147], v[12:13], v[110:111], v[126:127]
	v_pk_mul_f32 v[110:111], v[152:153], v[108:109] op_sel_hi:[1,0]
; template <bool HAS_H, bool HAS_XN, int XL, int XS>
; __device__ __forceinline__ void rowwise_phase(const float* xf, half_t* x16, float* xo, const half_t* hs, const float* nwA, const float* gvec, const float* nwB, const float* scv, const float* shv, half_t* xn, int gw, int NW, int lane) {
;     ...
;                 for (int j = 0; j < 4; ++j) xv[j] = xv[j] + gg[j] * (hv[j] * r * wA[j]);
;             }
;             if (XS == 1) {
;                 u32x2* xs = (u32x2*)(x16 + (size_t)m * D) + lane;
; #pragma unroll
;                 for (int j = 0; j < 4; ++j) { u32x2 pk; pk.x = pg8::pkh(xv[j][0], xv[j][1]); pk.y = pg8::pkh(xv[j][2], xv[j][3]); xs[64 * j] = pk; }
;             } else if (XS == 2) {
;                 f32x4* xs = (f32x4*)(xo + (size_t)m * D) + lane;
; #pragma unroll
;                 for (int j = 0; j < 4; ++j) xs[64 * j] = xv[j];
;             }
;             if (HAS_XN) {
;                 float ss = 0.f;
; #pragma unroll
;                 for (int j = 0; j < 4; ++j) ss += (xv[j][0] * xv[j][0] + xv[j][1] * xv[j][1]) + (xv[j][2] * xv[j][2] + xv[j][3] * xv[j][3]);
;                 const float r = 1.0f / sqrtf(wave_sum(ss) * (1.f / D) + RMS_EPS);
;                 u32x2* xo2 = (u32x2*)(xn + (size_t)m * D) + lane;
; #pragma unroll
;                 for (int j = 0; j < 4; ++j) { const f32x4 o = (xv[j] * r * wB[j]) * sc1[j] + sh[j]; u32x2 pk; pk.x = pg8::pkh(o[0], o[1]); pk.y = pg8::pkh(o[2], o[3]); xo2[64 * j] = pk; }
	v_pk_fma_f32 v[148:149], v[10:11], v[112:113], v[124:125]
	v_pk_mul_f32 v[112:113], v[150:151], v[108:109] op_sel_hi:[1,0]
	v_pk_mul_f32 v[110:111], v[8:9], v[110:111]
	v_pk_mul_f32 v[112:113], v[6:7], v[112:113]
	v_pk_fma_f32 v[126:127], v[16:17], v[110:111], v[134:135]
	v_pk_mul_f32 v[110:111], v[156:157], v[108:109] op_sel_hi:[1,0]
	v_pk_fma_f32 v[128:129], v[14:15], v[112:113], v[128:129]
	v_pk_mul_f32 v[112:113], v[154:155], v[108:109] op_sel_hi:[1,0]
	v_pk_mul_f32 v[110:111], v[36:37], v[110:111]
	v_pk_mul_f32 v[114:115], v[34:35], v[112:113]
	v_pk_fma_f32 v[112:113], v[44:45], v[110:111], v[136:137]
	v_pk_mul_f32 v[110:111], v[162:163], v[108:109] op_sel_hi:[1,0]
	v_pk_mul_f32 v[108:109], v[160:161], v[108:109] op_sel_hi:[1,0]
	v_pk_fma_f32 v[114:115], v[42:43], v[114:115], v[130:131]
	v_pk_mul_f32 v[124:125], v[38:39], v[108:109]
	v_pk_mul_f32 v[108:109], v[40:41], v[110:111]
	v_pk_fma_f32 v[110:111], v[46:47], v[124:125], v[132:133]
	v_cvt_pk_f16_f32 v210, v148, v149
	v_cvt_pk_f16_f32 v211, v146, v147
	v_cvt_pk_f16_f32 v212, v128, v129
	v_cvt_pk_f16_f32 v213, v126, v127
	v_pk_fma_f32 v[108:109], v[48:49], v[108:109], v[144:145]
	v_cvt_pk_f16_f32 v214, v114, v115
	v_cvt_pk_f16_f32 v215, v112, v113
	v_cvt_pk_f16_f32 v216, v110, v111
	v_cvt_pk_f16_f32 v217, v108, v109
	v_pk_mul_f32 v[124:125], v[146:147], v[146:147]
	v_pk_mul_f32 v[130:131], v[148:149], v[148:149]
	s_nop 0
	v_pk_mov_b32 v[132:133], v[130:131], v[124:125] op_sel:[1,0]
	v_mov_b32_e32 v131, v125
	v_pk_add_f32 v[124:125], v[132:133], v[130:131]
	v_pk_mul_f32 v[130:131], v[126:127], v[126:127]
	v_pk_add_f32 v[124:125], v[124:125], v[124:125] op_sel_hi:[0,1]
	v_pk_mul_f32 v[132:133], v[128:129], v[128:129]
	v_mul_f32_e32 v124, v114, v114
	v_pk_mov_b32 v[134:135], v[132:133], v[130:131] op_sel:[1,0]
	v_mov_b32_e32 v133, v131
	v_pk_add_f32 v[130:131], v[134:135], v[132:133]
	v_pk_fma_f32 v[132:133], v[114:115], v[114:115], v[124:125] op_sel_hi:[1,1,0]
	v_mul_f32_e32 v124, v112, v112
	v_pk_add_f32 v[130:131], v[130:131], v[130:131] op_sel_hi:[0,1]
	v_pk_fma_f32 v[134:135], v[112:113], v[112:113], v[124:125] op_sel_hi:[1,1,0]
	v_mul_f32_e32 v132, v110, v110
	v_mul_f32_e32 v134, v111, v111
	v_mul_f32_e32 v124, v108, v108
	v_mul_f32_e32 v130, v109, v109
	v_pk_add_f32 v[132:133], v[132:133], v[134:135]
	v_pk_add_f32 v[124:125], v[124:125], v[130:131]
	s_nop 0
	v_pk_add_f32 v[124:125], v[132:133], v[124:125]
	s_nop 0
	v_add_f32_e32 v124, v124, v125
	ds_bpermute_b32 v125, v83, v124
	s_waitcnt lgkmcnt(0)
	v_add_f32_e32 v124, v124, v125
	ds_bpermute_b32 v125, v138, v124
	s_waitcnt lgkmcnt(0)
	v_add_f32_e32 v124, v124, v125
	ds_bpermute_b32 v125, v139, v124
	s_waitcnt lgkmcnt(0)
	v_add_f32_e32 v124, v124, v125
	ds_bpermute_b32 v125, v140, v124
	s_waitcnt lgkmcnt(0)
	v_add_f32_e32 v124, v124, v125
	ds_bpermute_b32 v125, v141, v124
	s_waitcnt lgkmcnt(0)
	v_add_f32_e32 v124, v124, v125
	ds_bpermute_b32 v125, v142, v124
	s_waitcnt lgkmcnt(0)
	v_add_f32_e32 v124, v124, v125
	v_fmamk_f32 v124, v124, 0x3a800000, v201
	v_cmp_gt_f32_e32 vcc, s81, v124
	v_mul_f32_e32 v125, 0x4f800000, v124
	s_nop 0
	v_cndmask_b32_e32 v124, v124, v125, vcc
	v_sqrt_f32_e32 v125, v124
	s_nop 0
	v_add_u32_e32 v130, -1, v125
	v_fma_f32 v131, -v130, v125, v124
	v_cmp_ge_f32_e64 s[4:5], 0, v131
	v_add_u32_e32 v131, 1, v125
	s_nop 0
	v_cndmask_b32_e64 v130, v125, v130, s[4:5]
	v_fma_f32 v125, -v131, v125, v124
	v_cmp_lt_f32_e64 s[4:5], 0, v125
	s_nop 1
	v_cndmask_b32_e64 v125, v130, v131, s[4:5]
	v_mul_f32_e32 v130, 0x37800000, v125
	v_cndmask_b32_e32 v125, v125, v130, vcc
	v_cmp_class_f32_e32 vcc, v124, v202
	s_nop 1
	v_cndmask_b32_e32 v124, v125, v124, vcc
	v_div_scale_f32 v125, s[4:5], v124, v124, 1.0
	v_rcp_f32_e32 v130, v125
	s_nop 0
	v_fma_f32 v131, -v125, v130, 1.0
	v_fmac_f32_e32 v130, v131, v130
	v_div_scale_f32 v131, vcc, 1.0, v124, 1.0
	v_mul_f32_e32 v132, v131, v130
	v_fma_f32 v133, -v125, v132, v131
	v_fmac_f32_e32 v132, v133, v130
	v_fma_f32 v125, -v125, v132, v131
	v_div_fmas_f32 v125, v125, v130, v132
	v_div_fixup_f32 v124, v125, v124, 1.0
	v_pk_mul_f32 v[130:131], v[146:147], v[124:125] op_sel_hi:[1,0]
	v_pk_mul_f32 v[132:133], v[148:149], v[124:125] op_sel_hi:[1,0]
	v_pk_mul_f32 v[130:131], v[20:21], v[130:131]
	v_pk_mul_f32 v[132:133], v[18:19], v[132:133]
	v_pk_mul_f32 v[126:127], v[126:127], v[124:125] op_sel_hi:[1,0]
	v_pk_mul_f32 v[128:129], v[128:129], v[124:125] op_sel_hi:[1,0]
	v_pk_fma_f32 v[134:135], v[80:81], v[130:131], v[28:29]
	v_pk_fma_f32 v[130:131], v[78:79], v[132:133], v[26:27]
	v_add_co_u32_e32 v132, vcc, s57, v106
	v_pk_mul_f32 v[128:129], v[22:23], v[128:129]
	v_pk_mul_f32 v[126:127], v[24:25], v[126:127]
	v_addc_co_u32_e32 v133, vcc, -1, v107, vcc
	v_pk_fma_f32 v[126:127], v[72:73], v[126:127], v[32:33]
	v_pk_fma_f32 v[128:129], v[70:71], v[128:129], v[30:31]
	v_pk_mul_f32 v[112:113], v[112:113], v[124:125] op_sel_hi:[1,0]
	v_pk_mul_f32 v[114:115], v[114:115], v[124:125] op_sel_hi:[1,0]
	v_cvt_pk_f16_f32 v128, v128, v129
	v_cvt_pk_f16_f32 v129, v126, v127
	v_add_co_u32_e32 v126, vcc, s67, v106
	v_pk_mul_f32 v[114:115], v[50:51], v[114:115]
	v_pk_mul_f32 v[112:113], v[52:53], v[112:113]
	v_addc_co_u32_e32 v127, vcc, -1, v107, vcc
	v_pk_fma_f32 v[112:113], v[76:77], v[112:113], v[60:61]
	v_pk_fma_f32 v[114:115], v[74:75], v[114:115], v[58:59]
	v_pk_mul_f32 v[108:109], v[108:109], v[124:125] op_sel_hi:[1,0]
	v_pk_mul_f32 v[110:111], v[110:111], v[124:125] op_sel_hi:[1,0]
	v_cvt_pk_f16_f32 v114, v114, v115
	v_cvt_pk_f16_f32 v115, v112, v113
	v_add_co_u32_e32 v112, vcc, s95, v106
	v_pk_mul_f32 v[110:111], v[54:55], v[110:111]
	v_pk_mul_f32 v[108:109], v[56:57], v[108:109]
	v_addc_co_u32_e32 v113, vcc, -1, v107, vcc
	v_pk_fma_f32 v[108:109], v[68:69], v[108:109], v[64:65]
	v_pk_fma_f32 v[110:111], v[66:67], v[110:111], v[62:63]
	v_cvt_pk_f16_f32 v130, v130, v131
	v_cvt_pk_f16_f32 v110, v110, v111
	v_cvt_pk_f16_f32 v111, v108, v109
	v_add_co_u32_e32 v108, vcc, s76, v106
	v_cvt_pk_f16_f32 v131, v134, v135
	s_nop 0
	v_addc_co_u32_e32 v109, vcc, -1, v107, vcc
	s_waitcnt vmcnt(0)
	v_mov_b32_e32 v143, v101
	global_store_dwordx2 v[106:107], v[210:211], off
	global_store_dwordx2 v[106:107], v[212:213], off offset:512
	global_store_dwordx2 v[106:107], v[214:215], off offset:1024
	global_store_dwordx2 v[106:107], v[216:217], off offset:1536
	global_store_dwordx2 v[112:113], v[114:115], off
	global_store_dwordx2 v[108:109], v[110:111], off
	v_mov_b32_e32 v114, v122
	v_mov_b32_e32 v115, v123
	v_mov_b32_e32 v112, v120
	v_mov_b32_e32 v113, v121
	v_mov_b32_e32 v110, v118
	v_mov_b32_e32 v111, v119
	v_mov_b32_e32 v108, v116
	v_mov_b32_e32 v109, v117
	v_lshl_add_u64 v[106:107], v[106:107], 0, s[90:91]
	global_store_dwordx2 v[132:133], v[130:131], off
	global_store_dwordx2 v[126:127], v[128:129], off
	s_cbranch_scc0 .LBB0_1234
	s_branch .LBB0_1229

; template <bool HAS_H, bool HAS_XN, int XL, int XS>
; __device__ __forceinline__ void rowwise_phase(const float* xf, half_t* x16, float* xo, const half_t* hs, const float* nwA, const float* gvec, const float* nwB, const float* scv, const float* shv, half_t* xn, int gw, int NW, int lane) {
;     ...
;         f32x4 wA[4], gg[4], wB[4], sc1[4], sh[4];
; #pragma unroll
;         for (int j = 0; j < 4; ++j) {
;             if (HAS_H) { wA[j] = *((const f32x4*)nwA + lane + 64 * j); gg[j] = *((const f32x4*)(gvec + (size_t)b * 6144) + lane + 64 * j); }
;             if (HAS_XN) { wB[j] = *((const f32x4*)nwB + lane + 64 * j); sc1[j] = *((const f32x4*)(scv + (size_t)b * 6144) + lane + 64 * j) + 1.0f; sh[j] = *((const f32x4*)(shv + (size_t)b * 6144) + lane + 64 * j); }
;         }
;         const int mend = (b + 1) * S;
;         f32x4 xq[4]; half4 xh[4], hq[4];
;         {
;             const int m0 = b * S + gw;
;             if (m0 < mend) {
;                 if (XL == 0) { const f32x4* xr = (const f32x4*)(xf + (size_t)m0 * D) + lane;
; #pragma unroll
;                     for (int j = 0; j < 4; ++j) xq[j] = xr[64 * j]; }
;                 else { const half4* xr = (const half4*)(x16 + (size_t)m0 * D) + lane;
; #pragma unroll
;                     for (int j = 0; j < 4; ++j) xh[j] = xr[64 * j]; }
;                 if (HAS_H) { const half4* hr = (const half4*)(hs + (size_t)m0 * D) + lane;
; #pragma unroll
;                     for (int j = 0; j < 4; ++j) hq[j] = hr[64 * j]; }
;             }
.LBB0_1239:
	s_mul_i32 s84, s4, 0x1800
	s_lshl_b64 s[2:3], s[84:85], 2
	s_waitcnt vmcnt(0) lgkmcnt(0)
	v_lshl_add_u64 v[46:47], v[100:101], 0, s[2:3]
	v_lshl_add_u64 v[58:59], v[104:105], 0, s[2:3]
	v_lshl_add_u64 v[62:63], v[106:107], 0, s[2:3]
	global_load_dwordx4 v[2:5], v[98:99], off
	global_load_dwordx4 v[6:9], v[98:99], off offset:1024
	global_load_dwordx4 v[10:13], v[46:47], off
	global_load_dwordx4 v[14:17], v[46:47], off offset:1024
	global_load_dwordx4 v[18:21], v[102:103], off
	global_load_dwordx4 v[22:25], v[102:103], off offset:1024
	global_load_dwordx4 v[94:97], v[58:59], off
	global_load_dwordx4 v[86:89], v[58:59], off offset:1024
	global_load_dwordx4 v[26:29], v[62:63], off
	global_load_dwordx4 v[30:33], v[62:63], off offset:1024
	global_load_dwordx4 v[34:37], v[98:99], off offset:2048
	global_load_dwordx4 v[38:41], v[98:99], off offset:3072
	global_load_dwordx4 v[42:45], v[46:47], off offset:2048
	s_nop 0
	global_load_dwordx4 v[46:49], v[46:47], off offset:3072
	s_nop 0
	global_load_dwordx4 v[50:53], v[102:103], off offset:2048
	global_load_dwordx4 v[54:57], v[102:103], off offset:3072
	global_load_dwordx4 v[90:93], v[58:59], off offset:2048
	global_load_dwordx4 v[82:85], v[58:59], off offset:3072
	s_nop 0
	global_load_dwordx4 v[58:61], v[62:63], off offset:2048
	s_nop 0
	global_load_dwordx4 v[62:65], v[62:63], off offset:3072
	s_lshl_b32 s2, s4, 14
	v_cndmask_b32_e64 v0, 0, 1, s[6:7]
	v_cmp_ne_u32_e64 s[4:5], 1, v0
	s_andn2_b64 vcc, exec, s[6:7]
	s_add_i32 s10, s2, s22
	s_cbranch_vccnz .LBB0_1241
	s_ashr_i32 s11, s10, 31
	s_lshl_b64 s[12:13], s[10:11], 12
	v_lshl_add_u64 v[78:79], v[108:109], 0, s[12:13]
	s_lshl_b64 s[12:13], s[10:11], 11
	v_lshl_add_u64 v[120:121], v[110:111], 0, s[12:13]
	global_load_dwordx4 v[66:69], v[78:79], off
	global_load_dwordx4 v[70:73], v[78:79], off offset:1024
	global_load_dwordx4 v[74:77], v[78:79], off offset:2048
	s_nop 0
	global_load_dwordx4 v[78:81], v[78:79], off offset:3072
	s_nop 0
	global_load_dwordx2 v[114:115], v[120:121], off
	global_load_dwordx2 v[116:117], v[120:121], off offset:512
	global_load_dwordx2 v[118:119], v[120:121], off offset:1024
	s_nop 0
	global_load_dwordx2 v[120:121], v[120:121], off offset:1536

; template <bool HAS_H, bool HAS_XN, int XL, int XS>
; __device__ __forceinline__ void rowwise_phase(const float* xf, half_t* x16, float* xo, const half_t* hs, const float* nwA, const float* gvec, const float* nwB, const float* scv, const float* shv, half_t* xn, int gw, int NW, int lane) {
;     ...
;             f32x4 xv[4]; half4 hcur[4];
; #pragma unroll
;             for (int j = 0; j < 4; ++j) { if (XL == 0) xv[j] = xq[j]; else xv[j] = (f32x4){(float)xh[j][0], (float)xh[j][1], (float)xh[j][2], (float)xh[j][3]}; if (HAS_H) hcur[j] = hq[j]; }
;             const int mn = (m + NW < mend) ? m + NW : m;
;             {
;                 if (XL == 0) { const f32x4* xr = (const f32x4*)(xf + (size_t)mn * D) + lane;
; #pragma unroll
;                     for (int j = 0; j < 4; ++j) xq[j] = xr[64 * j]; }
;                 else { const half4* xr = (const half4*)(x16 + (size_t)mn * D) + lane;
; #pragma unroll
;                     for (int j = 0; j < 4; ++j) xh[j] = xr[64 * j]; }
;                 if (HAS_H) { const half4* hr = (const half4*)(hs + (size_t)mn * D) + lane;
; #pragma unroll
;                     for (int j = 0; j < 4; ++j) hq[j] = hr[64 * j]; }
;             }
;             if (HAS_H) {
;                 f32x4 hv[4]; float ss = 0.f;
; #pragma unroll
;                 for (int j = 0; j < 4; ++j) { const half4 h4 = hcur[j]; hv[j] = (f32x4){(float)h4[0], (float)h4[1], (float)h4[2], (float)h4[3]}; ss += (hv[j][0] * hv[j][0] + hv[j][1] * hv[j][1]) + (hv[j][2] * hv[j][2] + hv[j][3] * hv[j][3]); }
;                 const float r = 1.0f / sqrtf(wave_sum(ss) * (1.f / D) + RMS_EPS);
.LBB0_1243:
	v_mov_b64_e32 v[152:153], v[114:115]
	v_cvt_f32_f16_sdwa v155, v152 dst_sel:DWORD dst_unused:UNUSED_PAD src0_sel:WORD_1
	v_cvt_f32_f16_sdwa v157, v153 dst_sel:DWORD dst_unused:UNUSED_PAD src0_sel:WORD_1
	v_cvt_f32_f16_e32 v154, v152
	v_cvt_f32_f16_e32 v156, v153
	v_mov_b32_e32 v158, v155
	v_mov_b32_e32 v159, v157
	v_mov_b64_e32 v[150:151], v[116:117]
	v_mov_b32_e32 v152, v154
	v_mov_b32_e32 v153, v156
	v_pk_mul_f32 v[158:159], v[158:159], v[158:159]
	v_cvt_f32_f16_sdwa v161, v151 dst_sel:DWORD dst_unused:UNUSED_PAD src0_sel:WORD_1
	v_pk_fma_f32 v[152:153], v[152:153], v[152:153], v[158:159]
	v_cvt_f32_f16_sdwa v159, v150 dst_sel:DWORD dst_unused:UNUSED_PAD src0_sel:WORD_1
	v_cvt_f32_f16_e32 v158, v150
	v_cvt_f32_f16_e32 v160, v151
	v_mov_b32_e32 v163, v161
	v_mov_b32_e32 v162, v159
	v_mov_b64_e32 v[142:143], v[118:119]
	v_mov_b32_e32 v150, v158
	v_mov_b32_e32 v151, v160
	v_pk_mul_f32 v[162:163], v[162:163], v[162:163]
	v_mov_b64_e32 v[140:141], v[120:121]
	v_pk_fma_f32 v[150:151], v[150:151], v[150:151], v[162:163]
	v_cvt_f32_f16_sdwa v163, v142 dst_sel:DWORD dst_unused:UNUSED_PAD src0_sel:WORD_1
	v_cvt_f32_f16_e32 v162, v142
	v_cvt_f32_f16_sdwa v165, v143 dst_sel:DWORD dst_unused:UNUSED_PAD src0_sel:WORD_1
	v_cvt_f32_f16_e32 v164, v143
	v_cvt_f32_f16_sdwa v169, v140 dst_sel:DWORD dst_unused:UNUSED_PAD src0_sel:WORD_1
	v_cvt_f32_f16_e32 v168, v140
	v_cvt_f32_f16_sdwa v181, v141 dst_sel:DWORD dst_unused:UNUSED_PAD src0_sel:WORD_1
	v_cvt_f32_f16_e32 v180, v141
	v_mul_f32_e32 v0, v163, v163
	v_pk_fma_f32 v[142:143], v[162:163], v[162:163], v[0:1] op_sel_hi:[1,1,0]
	v_mul_f32_e32 v0, v165, v165
	v_pk_add_f32 v[152:153], v[152:153], v[152:153] op_sel:[0,1] op_sel_hi:[1,0]
	v_pk_add_f32 v[150:151], v[150:151], v[150:151] op_sel:[0,1] op_sel_hi:[1,0]
	v_pk_fma_f32 v[166:167], v[164:165], v[164:165], v[0:1] op_sel_hi:[1,1,0]
	v_pk_mul_f32 v[140:141], v[168:169], v[168:169]
	v_pk_mul_f32 v[182:183], v[180:181], v[180:181]
	v_mov_b32_e32 v153, v140
	v_mov_b32_e32 v151, v141
	v_mov_b32_e32 v143, v182
	v_mov_b32_e32 v167, v183
	v_pk_add_f32 v[140:141], v[152:153], v[150:151]
	v_pk_add_f32 v[142:143], v[142:143], v[166:167]
	s_add_i32 s3, s10, s80
	v_pk_add_f32 v[140:141], v[140:141], v[142:143]
	s_cmp_lt_i32 s3, s2
	v_add_f32_e32 v0, v140, v141
	ds_bpermute_b32 v140, v144, v0
	s_cselect_b32 s4, s3, s10
	s_ashr_i32 s5, s4, 31
	s_lshl_b64 s[10:11], s[4:5], 12
	s_lshl_b64 s[4:5], s[4:5], 11
	s_waitcnt lgkmcnt(0)
	v_add_f32_e32 v0, v0, v140
	ds_bpermute_b32 v140, v145, v0
	v_lshl_add_u64 v[120:121], v[110:111], 0, s[4:5]
	v_lshl_add_u64 v[82:83], v[108:109], 0, s[10:11]
	global_load_dwordx4 v[94:97], v[82:83], off
	global_load_dwordx4 v[90:93], v[82:83], off offset:1024
	global_load_dwordx4 v[86:89], v[82:83], off offset:2048
	s_nop 0
	global_load_dwordx4 v[82:85], v[82:83], off offset:3072
	s_nop 0
	global_load_dwordx2 v[114:115], v[120:121], off
	global_load_dwordx2 v[116:117], v[120:121], off offset:512
	global_load_dwordx2 v[118:119], v[120:121], off offset:1024
	s_nop 0
	global_load_dwordx2 v[120:121], v[120:121], off offset:1536
	s_waitcnt lgkmcnt(0)
	v_add_f32_e32 v0, v0, v140
	ds_bpermute_b32 v140, v146, v0
	s_cmp_ge_i32 s3, s2
	s_mov_b32 s10, s3
	s_waitcnt lgkmcnt(0)
	v_add_f32_e32 v0, v0, v140
	ds_bpermute_b32 v140, v147, v0
	s_waitcnt lgkmcnt(0)
	v_add_f32_e32 v0, v0, v140
	ds_bpermute_b32 v140, v148, v0
	s_waitcnt lgkmcnt(0)
	v_add_f32_e32 v0, v0, v140
	ds_bpermute_b32 v140, v149, v0
	s_waitcnt lgkmcnt(0)
	v_add_f32_e32 v0, v0, v140
	v_fmamk_f32 v0, v0, 0x3a800000, v201
	v_cmp_gt_f32_e32 vcc, s81, v0
	v_mul_f32_e32 v140, 0x4f800000, v0
	s_nop 0
	v_cndmask_b32_e32 v0, v0, v140, vcc
	v_sqrt_f32_e32 v140, v0
	s_nop 0
	v_add_u32_e32 v141, -1, v140
	v_fma_f32 v142, -v141, v140, v0
	v_cmp_ge_f32_e64 s[4:5], 0, v142
	v_add_u32_e32 v142, 1, v140
	s_nop 0
	v_cndmask_b32_e64 v141, v140, v141, s[4:5]
	v_fma_f32 v140, -v142, v140, v0
	v_cmp_lt_f32_e64 s[4:5], 0, v140
	s_nop 1
	v_cndmask_b32_e64 v140, v141, v142, s[4:5]
	v_mul_f32_e32 v141, 0x37800000, v140
	v_cndmask_b32_e32 v140, v140, v141, vcc
	v_cmp_class_f32_e32 vcc, v0, v202
	s_nop 1
	v_cndmask_b32_e32 v0, v140, v0, vcc
	v_div_scale_f32 v140, s[4:5], v0, v0, 1.0
	v_rcp_f32_e32 v141, v140
	s_nop 0
	v_fma_f32 v142, -v140, v141, 1.0
	v_fmac_f32_e32 v141, v142, v141
	v_div_scale_f32 v142, vcc, 1.0, v0, 1.0
	v_mul_f32_e32 v143, v142, v141
	v_fma_f32 v150, -v140, v143, v142
	v_fmac_f32_e32 v143, v150, v141
	v_fma_f32 v140, -v140, v143, v142
	v_div_fmas_f32 v140, v140, v141, v143
	v_div_fixup_f32 v0, v140, v0, 1.0
	v_pk_mul_f32 v[140:141], v[156:157], v[0:1] op_sel_hi:[1,0]
	v_pk_mul_f32 v[142:143], v[154:155], v[0:1] op_sel_hi:[1,0]
	v_pk_mul_f32 v[140:141], v[4:5], v[140:141]
	v_pk_mul_f32 v[142:143], v[2:3], v[142:143]
	v_pk_fma_f32 v[150:151], v[12:13], v[140:141], v[68:69]
	v_pk_fma_f32 v[152:153], v[10:11], v[142:143], v[66:67]
	v_pk_mul_f32 v[66:67], v[160:161], v[0:1] op_sel_hi:[1,0]
	v_pk_mul_f32 v[68:69], v[158:159], v[0:1] op_sel_hi:[1,0]
	v_pk_mul_f32 v[66:67], v[8:9], v[66:67]
	v_pk_mul_f32 v[68:69], v[6:7], v[68:69]
	v_pk_fma_f32 v[140:141], v[16:17], v[66:67], v[72:73]
	v_pk_fma_f32 v[142:143], v[14:15], v[68:69], v[70:71]
	v_pk_mul_f32 v[66:67], v[164:165], v[0:1] op_sel_hi:[1,0]
	v_pk_mul_f32 v[68:69], v[162:163], v[0:1] op_sel_hi:[1,0]
	v_pk_mul_f32 v[66:67], v[36:37], v[66:67]
	v_pk_mul_f32 v[68:69], v[34:35], v[68:69]
	v_pk_fma_f32 v[70:71], v[44:45], v[66:67], v[76:77]
	v_pk_fma_f32 v[72:73], v[42:43], v[68:69], v[74:75]
	v_pk_mul_f32 v[66:67], v[180:181], v[0:1] op_sel_hi:[1,0]
	v_pk_mul_f32 v[68:69], v[168:169], v[0:1] op_sel_hi:[1,0]
	v_cvt_pk_f16_f32 v74, v152, v153
; template <bool HAS_H, bool HAS_XN, int XL, int XS>
; __device__ __forceinline__ void rowwise_phase(const float* xf, half_t* x16, float* xo, const half_t* hs, const float* nwA, const float* gvec, const float* nwB, const float* scv, const float* shv, half_t* xn, int gw, int NW, int lane) {
;     ...
;                 for (int j = 0; j < 4; ++j) xv[j] = xv[j] + gg[j] * (hv[j] * r * wA[j]);
;             }
;             if (XS == 1) {
;                 u32x2* xs = (u32x2*)(x16 + (size_t)m * D) + lane;
; #pragma unroll
;                 for (int j = 0; j < 4; ++j) { u32x2 pk; pk.x = pg8::pkh(xv[j][0], xv[j][1]); pk.y = pg8::pkh(xv[j][2], xv[j][3]); xs[64 * j] = pk; }
;             } else if (XS == 2) {
;                 f32x4* xs = (f32x4*)(xo + (size_t)m * D) + lane;
; #pragma unroll
;                 for (int j = 0; j < 4; ++j) xs[64 * j] = xv[j];
;             }
;             if (HAS_XN) {
;                 float ss = 0.f;
; #pragma unroll
;                 for (int j = 0; j < 4; ++j) ss += (xv[j][0] * xv[j][0] + xv[j][1] * xv[j][1]) + (xv[j][2] * xv[j][2] + xv[j][3] * xv[j][3]);
;                 const float r = 1.0f / sqrtf(wave_sum(ss) * (1.f / D) + RMS_EPS);
;                 u32x2* xo2 = (u32x2*)(xn + (size_t)m * D) + lane;
; #pragma unroll
;                 for (int j = 0; j < 4; ++j) { const f32x4 o = (xv[j] * r * wB[j]) * sc1[j] + sh[j]; u32x2 pk; pk.x = pg8::pkh(o[0], o[1]); pk.y = pg8::pkh(o[2], o[3]); xo2[64 * j] = pk; }
	v_cvt_pk_f16_f32 v75, v150, v151
	v_pk_mul_f32 v[68:69], v[38:39], v[68:69]
	v_pk_mul_f32 v[66:67], v[40:41], v[66:67]
	global_store_dwordx2 v[138:139], v[74:75], off
	v_cvt_pk_f16_f32 v74, v142, v143
	v_cvt_pk_f16_f32 v75, v140, v141
	v_pk_fma_f32 v[66:67], v[48:49], v[66:67], v[80:81]
	v_pk_fma_f32 v[68:69], v[46:47], v[68:69], v[78:79]
	global_store_dwordx2 v[138:139], v[74:75], off offset:512
	v_cvt_pk_f16_f32 v74, v72, v73
	v_cvt_pk_f16_f32 v75, v70, v71
	global_store_dwordx2 v[138:139], v[74:75], off offset:1024
	v_cvt_pk_f16_f32 v74, v68, v69
	v_cvt_pk_f16_f32 v75, v66, v67
	global_store_dwordx2 v[138:139], v[74:75], off offset:1536
	v_pk_mul_f32 v[74:75], v[150:151], v[150:151]
	v_pk_mul_f32 v[76:77], v[152:153], v[152:153]
	v_mul_f32_e32 v0, v72, v72
	v_pk_mov_b32 v[78:79], v[76:77], v[74:75] op_sel:[1,0]
	v_mov_b32_e32 v77, v75
	v_pk_add_f32 v[74:75], v[78:79], v[76:77]
	v_pk_mul_f32 v[76:77], v[140:141], v[140:141]
	v_pk_mul_f32 v[78:79], v[142:143], v[142:143]
	v_pk_add_f32 v[74:75], v[74:75], v[74:75] op_sel_hi:[0,1]
	v_pk_mov_b32 v[80:81], v[78:79], v[76:77] op_sel:[1,0]
	v_mov_b32_e32 v79, v77
	v_pk_add_f32 v[76:77], v[80:81], v[78:79]
	v_pk_fma_f32 v[78:79], v[72:73], v[72:73], v[0:1] op_sel_hi:[1,1,0]
	v_mul_f32_e32 v0, v70, v70
	v_pk_add_f32 v[76:77], v[76:77], v[76:77] op_sel_hi:[0,1]
	v_pk_fma_f32 v[80:81], v[70:71], v[70:71], v[0:1] op_sel_hi:[1,1,0]
	v_mul_f32_e32 v78, v68, v68
	v_mul_f32_e32 v80, v69, v69
	v_mul_f32_e32 v74, v66, v66
	v_mul_f32_e32 v76, v67, v67
	v_pk_add_f32 v[78:79], v[78:79], v[80:81]
	v_pk_add_f32 v[74:75], v[74:75], v[76:77]
	s_waitcnt vmcnt(0)
	v_mov_b32_e32 v80, v84
	v_pk_add_f32 v[74:75], v[78:79], v[74:75]
	v_mov_b32_e32 v81, v85
	v_add_f32_e32 v0, v74, v75
	ds_bpermute_b32 v74, v144, v0
	s_waitcnt lgkmcnt(0)
	v_add_f32_e32 v0, v0, v74
	ds_bpermute_b32 v74, v145, v0
	s_waitcnt lgkmcnt(0)
	v_add_f32_e32 v0, v0, v74
	ds_bpermute_b32 v74, v146, v0
	s_waitcnt lgkmcnt(0)
	v_add_f32_e32 v0, v0, v74
	ds_bpermute_b32 v74, v147, v0
	s_waitcnt lgkmcnt(0)
	v_add_f32_e32 v0, v0, v74
	ds_bpermute_b32 v74, v148, v0
	s_waitcnt lgkmcnt(0)
	v_add_f32_e32 v0, v0, v74
	ds_bpermute_b32 v74, v149, v0
	s_waitcnt lgkmcnt(0)
	v_add_f32_e32 v0, v0, v74
	v_fmamk_f32 v0, v0, 0x3a800000, v201
	v_cmp_gt_f32_e32 vcc, s81, v0
	v_mul_f32_e32 v74, 0x4f800000, v0
	s_nop 0
	v_cndmask_b32_e32 v0, v0, v74, vcc
	v_sqrt_f32_e32 v74, v0
	s_nop 0
	v_add_u32_e32 v75, -1, v74
	v_fma_f32 v76, -v75, v74, v0
	v_cmp_ge_f32_e64 s[4:5], 0, v76
	v_add_u32_e32 v76, 1, v74
	s_nop 0
	v_cndmask_b32_e64 v75, v74, v75, s[4:5]
	v_fma_f32 v74, -v76, v74, v0
	v_cmp_lt_f32_e64 s[4:5], 0, v74
	s_nop 1
	v_cndmask_b32_e64 v74, v75, v76, s[4:5]
	v_mul_f32_e32 v75, 0x37800000, v74
	v_cndmask_b32_e32 v74, v74, v75, vcc
	v_cmp_class_f32_e32 vcc, v0, v202
	s_nop 1
	v_cndmask_b32_e32 v0, v74, v0, vcc
	v_div_scale_f32 v74, s[4:5], v0, v0, 1.0
	v_rcp_f32_e32 v75, v74
	s_nop 0
	v_fma_f32 v76, -v74, v75, 1.0
	v_fmac_f32_e32 v75, v76, v75
	v_div_scale_f32 v76, vcc, 1.0, v0, 1.0
	v_mul_f32_e32 v77, v76, v75
	v_fma_f32 v78, -v74, v77, v76
	v_fmac_f32_e32 v77, v78, v75
	v_fma_f32 v74, -v74, v77, v76
	v_div_fmas_f32 v74, v74, v75, v77
	v_div_fixup_f32 v0, v74, v0, 1.0
	v_pk_mul_f32 v[74:75], v[150:151], v[0:1] op_sel_hi:[1,0]
	v_pk_mul_f32 v[76:77], v[152:153], v[0:1] op_sel_hi:[1,0]
	v_pk_mul_f32 v[74:75], v[20:21], v[74:75]
	v_pk_mul_f32 v[76:77], v[18:19], v[76:77]
	v_pk_fma_f32 v[78:79], v[122:123], v[74:75], v[28:29]
	v_pk_fma_f32 v[74:75], v[124:125], v[76:77], v[26:27]
	v_add_co_u32_e32 v76, vcc, s57, v138
	v_cvt_pk_f16_f32 v74, v74, v75
	v_cvt_pk_f16_f32 v75, v78, v79
	v_addc_co_u32_e32 v77, vcc, -1, v139, vcc
	global_store_dwordx2 v[76:77], v[74:75], off
	v_pk_mul_f32 v[74:75], v[140:141], v[0:1] op_sel_hi:[1,0]
	v_pk_mul_f32 v[76:77], v[142:143], v[0:1] op_sel_hi:[1,0]
	v_pk_mul_f32 v[74:75], v[24:25], v[74:75]
	v_pk_mul_f32 v[76:77], v[22:23], v[76:77]
	v_pk_fma_f32 v[74:75], v[126:127], v[74:75], v[32:33]
	v_pk_fma_f32 v[76:77], v[128:129], v[76:77], v[30:31]
	v_pk_mul_f32 v[70:71], v[70:71], v[0:1] op_sel_hi:[1,0]
	v_pk_mul_f32 v[72:73], v[72:73], v[0:1] op_sel_hi:[1,0]
	v_cvt_pk_f16_f32 v76, v76, v77
	v_cvt_pk_f16_f32 v77, v74, v75
	v_add_co_u32_e32 v74, vcc, s67, v138
	v_pk_mul_f32 v[72:73], v[50:51], v[72:73]
	v_pk_mul_f32 v[70:71], v[52:53], v[70:71]
	v_addc_co_u32_e32 v75, vcc, -1, v139, vcc
	v_pk_fma_f32 v[70:71], v[130:131], v[70:71], v[60:61]
	v_pk_fma_f32 v[72:73], v[132:133], v[72:73], v[58:59]
	v_pk_mul_f32 v[66:67], v[66:67], v[0:1] op_sel_hi:[1,0]
	v_pk_mul_f32 v[68:69], v[68:69], v[0:1] op_sel_hi:[1,0]
	v_cvt_pk_f16_f32 v72, v72, v73
	v_cvt_pk_f16_f32 v73, v70, v71
	v_add_co_u32_e32 v70, vcc, s95, v138
	v_pk_mul_f32 v[68:69], v[54:55], v[68:69]
	v_pk_mul_f32 v[66:67], v[56:57], v[66:67]
	v_addc_co_u32_e32 v71, vcc, -1, v139, vcc
	v_pk_fma_f32 v[66:67], v[134:135], v[66:67], v[64:65]
	v_pk_fma_f32 v[68:69], v[136:137], v[68:69], v[62:63]
	global_store_dwordx2 v[74:75], v[76:77], off
	v_cvt_pk_f16_f32 v68, v68, v69
	v_cvt_pk_f16_f32 v69, v66, v67
	v_add_co_u32_e32 v66, vcc, s76, v138
	global_store_dwordx2 v[70:71], v[72:73], off
	s_nop 0
	v_addc_co_u32_e32 v67, vcc, -1, v139, vcc
	global_store_dwordx2 v[66:67], v[68:69], off
	v_mov_b32_e32 v66, v94
	v_mov_b32_e32 v67, v95
	v_mov_b32_e32 v68, v96
	v_mov_b32_e32 v69, v97
	v_mov_b32_e32 v70, v90
	v_mov_b32_e32 v71, v91
	v_mov_b32_e32 v72, v92
	v_mov_b32_e32 v73, v93
	v_mov_b32_e32 v74, v86
	v_mov_b32_e32 v75, v87
	v_mov_b32_e32 v76, v88
	v_mov_b32_e32 v77, v89
	v_mov_b32_e32 v78, v82
	v_mov_b32_e32 v79, v83
	v_lshl_add_u64 v[138:139], v[138:139], 0, s[90:91]
	s_cbranch_scc0 .LBB0_1243
	s_branch .LBB0_1238

; template <bool HAS_H, bool HAS_XN, int XL, int XS>
; __device__ __forceinline__ void rowwise_phase(const float* xf, half_t* x16, float* xo, const half_t* hs, const float* nwA, const float* gvec, const float* nwB, const float* scv, const float* shv, half_t* xn, int gw, int NW, int lane) {
;     ...
;         f32x4 wA[4], gg[4], wB[4], sc1[4], sh[4];
; #pragma unroll
;         for (int j = 0; j < 4; ++j) {
;             if (HAS_H) { wA[j] = *((const f32x4*)nwA + lane + 64 * j); gg[j] = *((const f32x4*)(gvec + (size_t)b * 6144) + lane + 64 * j); }
;             if (HAS_XN) { wB[j] = *((const f32x4*)nwB + lane + 64 * j); sc1[j] = *((const f32x4*)(scv + (size_t)b * 6144) + lane + 64 * j) + 1.0f; sh[j] = *((const f32x4*)(shv + (size_t)b * 6144) + lane + 64 * j); }
;         }
;         const int mend = (b + 1) * S;
;         f32x4 xq[4]; half4 xh[4], hq[4];
;         {
;             const int m0 = b * S + gw;
;             if (m0 < mend) {
;                 if (XL == 0) { const f32x4* xr = (const f32x4*)(xf + (size_t)m0 * D) + lane;
; #pragma unroll
;                     for (int j = 0; j < 4; ++j) xq[j] = xr[64 * j]; }
;                 else { const half4* xr = (const half4*)(x16 + (size_t)m0 * D) + lane;
; #pragma unroll
;                     for (int j = 0; j < 4; ++j) xh[j] = xr[64 * j]; }
;                 if (HAS_H) { const half4* hr = (const half4*)(hs + (size_t)m0 * D) + lane;
; #pragma unroll
;                     for (int j = 0; j < 4; ++j) hq[j] = hr[64 * j]; }
;             }
.LBB0_1537:
	s_mul_i32 s84, s4, 0x1800
	s_lshl_b64 s[2:3], s[84:85], 2
	s_waitcnt vmcnt(0) lgkmcnt(0)
	v_lshl_add_u64 v[46:47], v[86:87], 0, s[2:3]
	v_lshl_add_u64 v[58:59], v[92:93], 0, s[2:3]
	v_lshl_add_u64 v[62:63], v[90:91], 0, s[2:3]
	global_load_dwordx4 v[2:5], v[84:85], off
	global_load_dwordx4 v[6:9], v[84:85], off offset:1024
	global_load_dwordx4 v[10:13], v[46:47], off
	global_load_dwordx4 v[14:17], v[46:47], off offset:1024
	global_load_dwordx4 v[18:21], v[88:89], off
	global_load_dwordx4 v[22:25], v[88:89], off offset:1024
	global_load_dwordx4 v[78:81], v[58:59], off
	global_load_dwordx4 v[70:73], v[58:59], off offset:1024
	global_load_dwordx4 v[26:29], v[62:63], off
	global_load_dwordx4 v[30:33], v[62:63], off offset:1024
	global_load_dwordx4 v[34:37], v[84:85], off offset:2048
	global_load_dwordx4 v[38:41], v[84:85], off offset:3072
	global_load_dwordx4 v[42:45], v[46:47], off offset:2048
	s_nop 0
	global_load_dwordx4 v[46:49], v[46:47], off offset:3072
	s_nop 0
	global_load_dwordx4 v[50:53], v[88:89], off offset:2048
	global_load_dwordx4 v[54:57], v[88:89], off offset:3072
	global_load_dwordx4 v[74:77], v[58:59], off offset:2048
	global_load_dwordx4 v[66:69], v[58:59], off offset:3072
	s_nop 0
	global_load_dwordx4 v[58:61], v[62:63], off offset:2048
	s_nop 0
	global_load_dwordx4 v[62:65], v[62:63], off offset:3072
	s_lshl_b32 s2, s4, 14
	v_cndmask_b32_e64 v83, 0, 1, s[16:17]
	v_cmp_ne_u32_e64 s[4:5], 1, v83
	s_andn2_b64 vcc, exec, s[16:17]
	s_add_i32 s20, s2, s22
	s_cbranch_vccnz .LBB0_1539
	s_ashr_i32 s21, s20, 31
	s_lshl_b64 s[24:25], s[20:21], 11
	v_lshl_add_u64 v[100:101], v[94:95], 0, s[24:25]
	v_lshl_add_u64 v[106:107], v[96:97], 0, s[24:25]
	global_load_dwordx2 v[102:103], v[100:101], off
	global_load_dwordx2 v[104:105], v[100:101], off offset:512
	global_load_dwordx2 v[98:99], v[100:101], off offset:1024
	s_nop 0
	global_load_dwordx2 v[100:101], v[100:101], off offset:1536
	s_nop 0
	global_load_dwordx2 v[114:115], v[106:107], off
	global_load_dwordx2 v[112:113], v[106:107], off offset:512
	global_load_dwordx2 v[110:111], v[106:107], off offset:1024
	global_load_dwordx2 v[108:109], v[106:107], off offset:1536
	s_waitcnt vmcnt(0) lgkmcnt(0)
	v_mov_b32_e32 v143, v101

; template <bool HAS_H, bool HAS_XN, int XL, int XS>
; __device__ __forceinline__ void rowwise_phase(const float* xf, half_t* x16, float* xo, const half_t* hs, const float* nwA, const float* gvec, const float* nwB, const float* scv, const float* shv, half_t* xn, int gw, int NW, int lane) {
;     ...
;         f32x4 wA[4], gg[4], wB[4], sc1[4], sh[4];
; #pragma unroll
;         for (int j = 0; j < 4; ++j) {
;             if (HAS_H) { wA[j] = *((const f32x4*)nwA + lane + 64 * j); gg[j] = *((const f32x4*)(gvec + (size_t)b * 6144) + lane + 64 * j); }
;             if (HAS_XN) { wB[j] = *((const f32x4*)nwB + lane + 64 * j); sc1[j] = *((const f32x4*)(scv + (size_t)b * 6144) + lane + 64 * j) + 1.0f; sh[j] = *((const f32x4*)(shv + (size_t)b * 6144) + lane + 64 * j); }
;         }
;         const int mend = (b + 1) * S;
;         f32x4 xq[4]; half4 xh[4], hq[4];
;         {
;             const int m0 = b * S + gw;
;             if (m0 < mend) {
;                 if (XL == 0) { const f32x4* xr = (const f32x4*)(xf + (size_t)m0 * D) + lane;
; #pragma unroll
;                     for (int j = 0; j < 4; ++j) xq[j] = xr[64 * j]; }
;                 else { const half4* xr = (const half4*)(x16 + (size_t)m0 * D) + lane;
; #pragma unroll
;                     for (int j = 0; j < 4; ++j) xh[j] = xr[64 * j]; }
;                 if (HAS_H) { const half4* hr = (const half4*)(hs + (size_t)m0 * D) + lane;
; #pragma unroll
;                     for (int j = 0; j < 4; ++j) hq[j] = hr[64 * j]; }
;             }
.LBB0_1545:
	s_mul_i32 s84, s4, 0x1800
	s_waitcnt vmcnt(0) lgkmcnt(0)
	v_lshl_add_u64 v[30:31], s[84:85], 2, v[36:37]
	global_load_dwordx4 v[2:5], v[34:35], off
	global_load_dwordx4 v[6:9], v[34:35], off offset:1024
	global_load_dwordx4 v[10:13], v[30:31], off
	global_load_dwordx4 v[14:17], v[30:31], off offset:1024
	global_load_dwordx4 v[18:21], v[34:35], off offset:2048
	global_load_dwordx4 v[22:25], v[34:35], off offset:3072
	global_load_dwordx4 v[26:29], v[30:31], off offset:2048
	s_nop 0
	global_load_dwordx4 v[30:33], v[30:31], off offset:3072
	s_lshl_b32 s10, s4, 14
	v_cndmask_b32_e64 v0, 0, 1, s[6:7]
	v_cmp_ne_u32_e64 s[4:5], 1, v0
	s_andn2_b64 vcc, exec, s[6:7]
	s_add_i32 s2, s10, s22
	s_cbranch_vccnz .LBB0_1547
	s_ashr_i32 s3, s2, 31
	s_lshl_b64 s[12:13], s[2:3], 11
	v_lshl_add_u64 v[46:47], v[38:39], 0, s[12:13]
	v_lshl_add_u64 v[52:53], v[40:41], 0, s[12:13]
	global_load_dwordx2 v[48:49], v[46:47], off
	global_load_dwordx2 v[50:51], v[46:47], off offset:512
	global_load_dwordx2 v[44:45], v[46:47], off offset:1024
	s_nop 0
	global_load_dwordx2 v[46:47], v[46:47], off offset:1536
	s_nop 0
	global_load_dwordx2 v[58:59], v[52:53], off
	global_load_dwordx2 v[56:57], v[52:53], off offset:512
	global_load_dwordx2 v[54:55], v[52:53], off offset:1024
	s_nop 0
	global_load_dwordx2 v[52:53], v[52:53], off offset:1536
	s_waitcnt vmcnt(0) lgkmcnt(0)
	v_mov_b32_e32 v81, v47

; template <bool HAS_H, bool HAS_XN, int XL, int XS>
; __device__ __forceinline__ void rowwise_phase(const float* xf, half_t* x16, float* xo, const half_t* hs, const float* nwA, const float* gvec, const float* nwB, const float* scv, const float* shv, half_t* xn, int gw, int NW, int lane) {
;     ...
;             f32x4 xv[4]; half4 hcur[4];
; #pragma unroll
;             for (int j = 0; j < 4; ++j) { if (XL == 0) xv[j] = xq[j]; else xv[j] = (f32x4){(float)xh[j][0], (float)xh[j][1], (float)xh[j][2], (float)xh[j][3]}; if (HAS_H) hcur[j] = hq[j]; }
;             const int mn = (m + NW < mend) ? m + NW : m;
;             {
;                 if (XL == 0) { const f32x4* xr = (const f32x4*)(xf + (size_t)mn * D) + lane;
; #pragma unroll
;                     for (int j = 0; j < 4; ++j) xq[j] = xr[64 * j]; }
;                 else { const half4* xr = (const half4*)(x16 + (size_t)mn * D) + lane;
; #pragma unroll
;                     for (int j = 0; j < 4; ++j) xh[j] = xr[64 * j]; }
;                 if (HAS_H) { const half4* hr = (const half4*)(hs + (size_t)mn * D) + lane;
; #pragma unroll
;                     for (int j = 0; j < 4; ++j) hq[j] = hr[64 * j]; }
;             }
;             if (HAS_H) {
;                 f32x4 hv[4]; float ss = 0.f;
; #pragma unroll
;                 for (int j = 0; j < 4; ++j) { const half4 h4 = hcur[j]; hv[j] = (f32x4){(float)h4[0], (float)h4[1], (float)h4[2], (float)h4[3]}; ss += (hv[j][0] * hv[j][0] + hv[j][1] * hv[j][1]) + (hv[j][2] * hv[j][2] + hv[j][3] * hv[j][3]); }
;                 const float r = 1.0f / sqrtf(wave_sum(ss) * (1.f / D) + RMS_EPS);
; #pragma unroll
;                 for (int j = 0; j < 4; ++j) xv[j] = xv[j] + gg[j] * (hv[j] * r * wA[j]);
;             }
;             if (XS == 1) {
;                 u32x2* xs = (u32x2*)(x16 + (size_t)m * D) + lane;
; #pragma unroll
;                 for (int j = 0; j < 4; ++j) { u32x2 pk; pk.x = pg8::pkh(xv[j][0], xv[j][1]); pk.y = pg8::pkh(xv[j][2], xv[j][3]); xs[64 * j] = pk; }
;             } else if (XS == 2) {
;                 f32x4* xs = (f32x4*)(xo + (size_t)m * D) + lane;
; #pragma unroll
;                 for (int j = 0; j < 4; ++j) xs[64 * j] = xv[j];
.LBB0_1549:
	v_cvt_f32_f16_sdwa v93, v58 dst_sel:DWORD dst_unused:UNUSED_PAD src0_sel:WORD_1
	v_cvt_f32_f16_sdwa v95, v59 dst_sel:DWORD dst_unused:UNUSED_PAD src0_sel:WORD_1
	v_cvt_f32_f16_e32 v92, v58
	v_cvt_f32_f16_e32 v94, v59
	v_mov_b32_e32 v96, v93
	v_mov_b32_e32 v97, v95
	v_mov_b32_e32 v58, v92
	v_mov_b32_e32 v59, v94
	v_pk_mul_f32 v[96:97], v[96:97], v[96:97]
	v_cvt_f32_f16_sdwa v99, v57 dst_sel:DWORD dst_unused:UNUSED_PAD src0_sel:WORD_1
	v_pk_fma_f32 v[58:59], v[58:59], v[58:59], v[96:97]
	v_cvt_f32_f16_sdwa v97, v56 dst_sel:DWORD dst_unused:UNUSED_PAD src0_sel:WORD_1
	v_cvt_f32_f16_e32 v96, v56
	v_cvt_f32_f16_e32 v98, v57
	v_mov_b32_e32 v101, v99
	v_mov_b32_e32 v100, v97
	s_add_i32 s3, s2, s80
	v_mov_b32_e32 v56, v96
	v_mov_b32_e32 v57, v98
	v_pk_mul_f32 v[100:101], v[100:101], v[100:101]
	s_cmp_lt_i32 s3, s10
	v_pk_fma_f32 v[56:57], v[56:57], v[56:57], v[100:101]
	v_cvt_f32_f16_e32 v100, v54
	s_cselect_b32 s4, s3, s2
	v_cvt_f32_f16_sdwa v101, v54 dst_sel:DWORD dst_unused:UNUSED_PAD src0_sel:WORD_1
	s_ashr_i32 s5, s4, 31
	v_cvt_f32_f16_e32 v102, v55
	s_lshl_b64 s[4:5], s[4:5], 11
	v_cvt_f32_f16_sdwa v103, v55 dst_sel:DWORD dst_unused:UNUSED_PAD src0_sel:WORD_1
	v_cvt_f32_f16_sdwa v107, v52 dst_sel:DWORD dst_unused:UNUSED_PAD src0_sel:WORD_1
	v_cvt_f32_f16_e32 v106, v52
	v_cvt_f32_f16_sdwa v109, v53 dst_sel:DWORD dst_unused:UNUSED_PAD src0_sel:WORD_1
	v_cvt_f32_f16_e32 v108, v53
	v_cvt_f32_f16_sdwa v71, v46 dst_sel:DWORD dst_unused:UNUSED_PAD src0_sel:WORD_1
	v_cvt_f32_f16_e32 v70, v46
	v_lshl_add_u64 v[46:47], v[38:39], 0, s[4:5]
	v_lshl_add_u64 v[84:85], v[40:41], 0, s[4:5]
	v_mul_f32_e32 v54, v100, v100
	v_cvt_f32_f16_sdwa v63, v48 dst_sel:DWORD dst_unused:UNUSED_PAD src0_sel:WORD_1
	v_cvt_f32_f16_e32 v62, v48
	v_cvt_f32_f16_sdwa v69, v49 dst_sel:DWORD dst_unused:UNUSED_PAD src0_sel:WORD_1
	v_cvt_f32_f16_e32 v68, v49
	v_cvt_f32_f16_sdwa v65, v50 dst_sel:DWORD dst_unused:UNUSED_PAD src0_sel:WORD_1
	v_cvt_f32_f16_e32 v64, v50
	v_cvt_f32_f16_sdwa v73, v51 dst_sel:DWORD dst_unused:UNUSED_PAD src0_sel:WORD_1
	v_cvt_f32_f16_e32 v72, v51
	v_cvt_f32_f16_sdwa v67, v44 dst_sel:DWORD dst_unused:UNUSED_PAD src0_sel:WORD_1
	v_cvt_f32_f16_e32 v66, v44
	v_cvt_f32_f16_sdwa v75, v45 dst_sel:DWORD dst_unused:UNUSED_PAD src0_sel:WORD_1
	v_cvt_f32_f16_e32 v74, v45
	global_load_dwordx2 v[48:49], v[46:47], off
	global_load_dwordx2 v[50:51], v[46:47], off offset:512
	global_load_dwordx2 v[44:45], v[46:47], off offset:1024
	s_nop 0
	global_load_dwordx2 v[46:47], v[46:47], off offset:1536
	s_nop 0
	global_load_dwordx2 v[86:87], v[84:85], off
	global_load_dwordx2 v[88:89], v[84:85], off offset:512
	global_load_dwordx2 v[90:91], v[84:85], off offset:1024
	s_nop 0
	global_load_dwordx2 v[84:85], v[84:85], off offset:1536
	v_pk_fma_f32 v[54:55], v[100:101], v[100:101], v[54:55] op_sel_hi:[1,1,0]
	v_pk_add_f32 v[58:59], v[58:59], v[58:59] op_sel_hi:[0,1]
	v_mul_f32_e32 v54, v102, v102
	v_pk_add_f32 v[56:57], v[56:57], v[56:57] op_sel_hi:[0,1]
	v_pk_fma_f32 v[104:105], v[102:103], v[102:103], v[54:55] op_sel_hi:[1,1,0]
	v_pk_mul_f32 v[52:53], v[106:107], v[106:107]
	v_pk_mul_f32 v[110:111], v[108:109], v[108:109]
	v_mov_b32_e32 v54, v52
	v_mov_b32_e32 v104, v53
	v_mov_b32_e32 v58, v110
	v_mov_b32_e32 v56, v111
	v_pk_add_f32 v[52:53], v[54:55], v[104:105]
	v_pk_add_f32 v[54:55], v[58:59], v[56:57]
	v_cvt_f32_f16_sdwa v83, v81 dst_sel:DWORD dst_unused:UNUSED_PAD src0_sel:WORD_1
	v_pk_add_f32 v[52:53], v[52:53], v[54:55]
	v_cvt_f32_f16_e32 v82, v81
	v_add_f32_e32 v52, v52, v53
	ds_bpermute_b32 v53, v0, v52
	s_cmp_ge_i32 s3, s10
	s_mov_b32 s2, s3
	s_waitcnt lgkmcnt(0)
	v_add_f32_e32 v52, v52, v53
	ds_bpermute_b32 v53, v76, v52
	s_waitcnt lgkmcnt(0)
	v_add_f32_e32 v52, v52, v53
	ds_bpermute_b32 v53, v77, v52
	s_waitcnt lgkmcnt(0)
	v_add_f32_e32 v52, v52, v53
	ds_bpermute_b32 v53, v78, v52
	s_waitcnt lgkmcnt(0)
	v_add_f32_e32 v52, v52, v53
	ds_bpermute_b32 v53, v79, v52
	s_waitcnt lgkmcnt(0)
	v_add_f32_e32 v52, v52, v53
	ds_bpermute_b32 v53, v80, v52
	s_waitcnt lgkmcnt(0)
	v_add_f32_e32 v52, v52, v53
	v_fmamk_f32 v52, v52, 0x3a800000, v201
	v_cmp_gt_f32_e32 vcc, s81, v52
	v_mul_f32_e32 v53, 0x4f800000, v52
	s_waitcnt vmcnt(0)
	v_mov_b32_e32 v81, v47
	v_cndmask_b32_e32 v52, v52, v53, vcc
	v_sqrt_f32_e32 v53, v52
	s_nop 0
	v_add_u32_e32 v54, -1, v53
	v_fma_f32 v55, -v54, v53, v52
	v_cmp_ge_f32_e64 s[4:5], 0, v55
	v_add_u32_e32 v55, 1, v53
	s_nop 0
	v_cndmask_b32_e64 v54, v53, v54, s[4:5]
	v_fma_f32 v53, -v55, v53, v52
	v_cmp_lt_f32_e64 s[4:5], 0, v53
	s_nop 1
	v_cndmask_b32_e64 v53, v54, v55, s[4:5]
	v_mul_f32_e32 v54, 0x37800000, v53
	v_cndmask_b32_e32 v53, v53, v54, vcc
	v_cmp_class_f32_e32 vcc, v52, v202
	s_nop 1
	v_cndmask_b32_e32 v52, v53, v52, vcc
	v_div_scale_f32 v53, s[4:5], v52, v52, 1.0
	v_rcp_f32_e32 v54, v53
	s_nop 0
	v_fma_f32 v55, -v53, v54, 1.0
	v_fmac_f32_e32 v54, v55, v54
	v_div_scale_f32 v55, vcc, 1.0, v52, 1.0
	v_mul_f32_e32 v56, v55, v54
	v_fma_f32 v57, -v53, v56, v55
	v_fmac_f32_e32 v56, v57, v54
	v_fma_f32 v53, -v53, v56, v55
	v_div_fmas_f32 v53, v53, v54, v56
	v_div_fixup_f32 v104, v53, v52, 1.0
	v_pk_mul_f32 v[52:53], v[94:95], v[104:105] op_sel_hi:[1,0]
	v_pk_mul_f32 v[54:55], v[92:93], v[104:105] op_sel_hi:[1,0]
	v_pk_mul_f32 v[52:53], v[4:5], v[52:53]
	v_pk_mul_f32 v[56:57], v[2:3], v[54:55]
	v_pk_fma_f32 v[54:55], v[12:13], v[52:53], v[68:69]
	v_pk_fma_f32 v[52:53], v[10:11], v[56:57], v[62:63]
	v_pk_mul_f32 v[56:57], v[98:99], v[104:105] op_sel_hi:[1,0]
	v_pk_mul_f32 v[58:59], v[96:97], v[104:105] op_sel_hi:[1,0]
	v_pk_mul_f32 v[56:57], v[8:9], v[56:57]
	v_pk_mul_f32 v[62:63], v[6:7], v[58:59]
	v_pk_fma_f32 v[58:59], v[16:17], v[56:57], v[72:73]
	v_pk_fma_f32 v[56:57], v[14:15], v[62:63], v[64:65]
	v_pk_mul_f32 v[62:63], v[102:103], v[104:105] op_sel_hi:[1,0]
	v_pk_mul_f32 v[64:65], v[100:101], v[104:105] op_sel_hi:[1,0]
	v_pk_mul_f32 v[62:63], v[20:21], v[62:63]
	v_pk_mul_f32 v[68:69], v[18:19], v[64:65]
	v_pk_fma_f32 v[64:65], v[28:29], v[62:63], v[74:75]
	v_pk_fma_f32 v[62:63], v[26:27], v[68:69], v[66:67]
	v_pk_mul_f32 v[66:67], v[108:109], v[104:105] op_sel_hi:[1,0]
	v_pk_mul_f32 v[68:69], v[106:107], v[104:105] op_sel_hi:[1,0]
	v_pk_mul_f32 v[66:67], v[24:25], v[66:67]
	v_pk_mul_f32 v[72:73], v[22:23], v[68:69]
	v_pk_fma_f32 v[68:69], v[32:33], v[66:67], v[82:83]
	v_pk_fma_f32 v[66:67], v[30:31], v[72:73], v[70:71]
	global_store_dwordx4 v[60:61], v[52:55], off offset:-2048
	global_store_dwordx4 v[60:61], v[56:59], off offset:-1024
	global_store_dwordx4 v[60:61], v[62:65], off
	global_store_dwordx4 v[60:61], v[66:69], off offset:1024
	v_mov_b32_e32 v58, v86
	v_mov_b32_e32 v59, v87
	v_mov_b32_e32 v56, v88
	v_mov_b32_e32 v57, v89
	v_mov_b32_e32 v54, v90
	v_mov_b32_e32 v55, v91
	v_mov_b32_e32 v52, v84
	v_mov_b32_e32 v53, v85
	v_lshl_add_u64 v[60:61], v[60:61], 0, s[58:59]
	s_cbranch_scc0 .LBB0_1549
	s_branch .LBB0_1544
